# v62 + instruction trims on serial attention streams: NSA window latch copies paired into 16 v_mov_b64; SWA row sum kept per-lane (sink term split 0.5+0.5), one exchange per item
# speedup vs baseline: 1.0012x; 1.0009x over previous
; DI unsigned pack2(float a, float b) { f32x2_t v = {a, b}; bf16x2_t r = __builtin_convertvector(v, bf16x2_t); return __builtin_bit_cast(unsigned, r); }
; DI float bflo(unsigned u) { return __uint_as_float(u << 16); }
; DI float bfhi(unsigned u) { return __uint_as_float(u & 0xffff0000u); }
; DI float siluf_(float x) { return x * __builtin_amdgcn_rcpf(1.f + __expf(-x)); }
; DI void attn_write_staged(const f32x16& o0, const f32x16& o1, bf16_t* og, const bf16_t* z, size_t tok0, int head, int lane, bf16_t* wl) {
;   const int q = lane & 31, h = lane >> 5;
; #pragma unroll
;   for (int dt = 0; dt < 2; ++dt)
; #pragma unroll
;     for (int q4 = 0; q4 < 4; ++q4) {
;       const f32x16& o = dt ? o1 : o0;
;       *(uint2*)(wl + q * 72 + dt * 32 + 8 * q4 + 4 * h) = make_uint2(pack2(o[4 * q4], o[4 * q4 + 1]), pack2(o[4 * q4 + 2], o[4 * q4 + 3]));
;     }
; #pragma unroll
;   for (int k = 0; k < 4; ++k) {
;     const int ci = lane + 64 * k, row = ci >> 3, c8 = ci & 7;
;     const u32x4 ov = *(const u32x4*)(wl + row * 72 + c8 * 8);
;     const size_t off = (tok0 + row) * 1024 + head * 64 + c8 * 8;
;     const u32x4 zv = ldg16(z + off);
;     u32x4 r;
;     r.x = pack2(bflo(ov.x) * siluf_(bflo(zv.x)), bfhi(ov.x) * siluf_(bfhi(zv.x)));
;     r.y = pack2(bflo(ov.y) * siluf_(bflo(zv.y)), bfhi(ov.y) * siluf_(bfhi(zv.y)));
;     r.z = pack2(bflo(ov.z) * siluf_(bflo(zv.z)), bfhi(ov.z) * siluf_(bfhi(zv.z)));
;     r.w = pack2(bflo(ov.w) * siluf_(bflo(zv.w)), bfhi(ov.w) * siluf_(bfhi(zv.w)));
;     *(u32x4*)(og + off) = r;
;   }
; DI void phase_attn_swa(const Params& P, const float* sinks, bf16_t* og, unsigned char* smem, int L, int G) {
;     ...
;     const float il = 1.f / l;
; #pragma unroll
;     for (int q = 0; q < 16; ++q) { o0[q] *= il; o1[q] *= il; }
;     attn_write_staged(o0, o1, og, big + SW_Z, (size_t)b * SEQ + t0, head, lane, (bf16_t*)(smem + 40960) + w * (32 * 72));
.LBB0_336:
	v_mov_b32_e32 v15, 0
	v_mov_b32_e32 v34, 0.5
	v_mov_b32_e32 v14, v15
	v_mov_b32_e32 v13, v15
	v_mov_b32_e32 v12, v15
	v_mov_b32_e32 v11, v15
	v_mov_b32_e32 v10, v15
	v_mov_b32_e32 v9, v15
	v_mov_b32_e32 v8, v15
	v_mov_b32_e32 v7, v15
	v_mov_b32_e32 v6, v15
	v_mov_b32_e32 v5, v15
	v_mov_b32_e32 v4, v15
	v_mov_b32_e32 v3, v15
	v_mov_b32_e32 v2, v15
	v_mov_b32_e32 v1, v15
	v_mov_b32_e32 v0, v15
	v_mov_b32_e32 v31, v15
	v_mov_b32_e32 v30, v15
	v_mov_b32_e32 v29, v15
	v_mov_b32_e32 v28, v15
	v_mov_b32_e32 v27, v15
	v_mov_b32_e32 v26, v15
	v_mov_b32_e32 v25, v15
	v_mov_b32_e32 v24, v15
	v_mov_b32_e32 v23, v15
	v_mov_b32_e32 v22, v15
	v_mov_b32_e32 v21, v15
	v_mov_b32_e32 v20, v15
	v_mov_b32_e32 v19, v15
	v_mov_b32_e32 v18, v15
	v_mov_b32_e32 v17, v15
	v_mov_b32_e32 v16, v15
.LBB0_337:
	v_lshlrev_b32_e32 v35, 2, v169
	ds_bpermute_b32 v35, v35, v34
	s_waitcnt lgkmcnt(0)
	v_add_f32_e32 v34, v34, v35
	s_mov_b32 s41, s39
	v_lshlrev_b32_e32 v35, 6, v173
	v_lshl_add_u64 v[32:33], v[148:149], 0, s[40:41]
	v_or_b32_e32 v35, v35, v130
	v_or_b32_e32 v36, v32, v132
	v_mov_b32_e32 v37, v33
	v_lshlrev_b64 v[40:41], 11, v[36:37]
	v_lshlrev_b32_e32 v35, 1, v35
	v_or_b32_e32 v40, v40, v35
	v_lshl_add_u64 v[36:37], s[36:37], 0, v[40:41]
	v_mov_b32_e32 v254, 0x4000
	v_mov_b32_e32 v255, 0
	v_lshl_add_u64 v[248:249], v[36:37], 0, v[254:255]
	v_lshl_add_u64 v[250:251], v[248:249], 0, v[254:255]
	v_lshl_add_u64 v[252:253], v[250:251], 0, v[254:255]
	global_load_dwordx4 v[36:39], v[36:37], off
	global_load_dwordx4 v[96:99], v[248:249], off
	global_load_dwordx4 v[100:103], v[250:251], off
	global_load_dwordx4 v[104:107], v[252:253], off
	v_div_scale_f32 v42, s[0:1], v34, v34, 1.0
	v_rcp_f32_e32 v43, v42
	v_div_scale_f32 v44, vcc, 1.0, v34, 1.0
	v_add_u32_e32 v45, 0xa000, v166
	v_fma_f32 v46, -v42, v43, 1.0
	v_fmac_f32_e32 v43, v46, v43
	v_mul_f32_e32 v46, v44, v43
	v_fma_f32 v47, -v42, v46, v44
	v_fmac_f32_e32 v46, v47, v43
	v_fma_f32 v42, -v42, v46, v44
	v_div_fmas_f32 v42, v42, v43, v46
	v_div_fixup_f32 v34, v42, v34, 1.0
	v_pk_mul_f32 v[0:1], v[34:35], v[0:1] op_sel_hi:[0,1]
	v_pk_mul_f32 v[2:3], v[34:35], v[2:3] op_sel_hi:[0,1]
	v_pk_mul_f32 v[4:5], v[34:35], v[4:5] op_sel_hi:[0,1]
	v_pk_mul_f32 v[20:21], v[20:21], v[34:35] op_sel_hi:[1,0]
	v_pk_mul_f32 v[6:7], v[34:35], v[6:7] op_sel_hi:[0,1]
	v_pk_mul_f32 v[22:23], v[22:23], v[34:35] op_sel_hi:[1,0]
	v_pk_mul_f32 v[24:25], v[24:25], v[34:35] op_sel_hi:[1,0]
	v_pk_mul_f32 v[10:11], v[34:35], v[10:11] op_sel_hi:[0,1]
	v_pk_mul_f32 v[26:27], v[26:27], v[34:35] op_sel_hi:[1,0]
	v_pk_mul_f32 v[12:13], v[34:35], v[12:13] op_sel_hi:[0,1]
	v_pk_mul_f32 v[16:17], v[16:17], v[34:35] op_sel_hi:[1,0]
	v_pk_mul_f32 v[18:19], v[18:19], v[34:35] op_sel_hi:[1,0]
	v_pk_mul_f32 v[8:9], v[34:35], v[8:9] op_sel_hi:[0,1]
	v_pk_mul_f32 v[28:29], v[28:29], v[34:35] op_sel_hi:[1,0]
	v_pk_mul_f32 v[14:15], v[34:35], v[14:15] op_sel_hi:[0,1]
	v_pk_mul_f32 v[30:31], v[30:31], v[34:35] op_sel_hi:[1,0]
	v_cvt_pk_bf16_f32 v0, v0, v1
	v_cvt_pk_bf16_f32 v1, v2, v3
	v_cvt_pk_bf16_f32 v2, v4, v5
	v_cvt_pk_bf16_f32 v3, v6, v7
	v_cvt_pk_bf16_f32 v5, v10, v11
	v_cvt_pk_bf16_f32 v6, v12, v13
	v_cvt_pk_bf16_f32 v10, v20, v21
	v_cvt_pk_bf16_f32 v11, v22, v23
	v_cvt_pk_bf16_f32 v12, v24, v25
	v_cvt_pk_bf16_f32 v13, v26, v27
	v_cvt_pk_bf16_f32 v4, v8, v9
	v_cvt_pk_bf16_f32 v7, v14, v15
	v_cvt_pk_bf16_f32 v8, v16, v17
	v_cvt_pk_bf16_f32 v9, v18, v19
	v_cvt_pk_bf16_f32 v14, v28, v29
	v_cvt_pk_bf16_f32 v15, v30, v31
	ds_write2_b64 v45, v[0:1], v[2:3] offset1:2
	ds_write2_b64 v45, v[4:5], v[6:7] offset0:4 offset1:6
	ds_write2_b64 v45, v[8:9], v[10:11] offset0:8 offset1:10
	ds_write2_b64 v45, v[12:13], v[14:15] offset0:12 offset1:14
	ds_read_b128 v[0:3], v167 offset:40960
	ds_read_b128 v[4:7], v167 offset:42112
	s_add_i32 s45, s45, s74
	s_cmpk_gt_i32 s45, 0xfff
	s_waitcnt lgkmcnt(1)
	v_lshlrev_b32_e32 v8, 16, v0
	v_and_b32_e32 v9, 0xffff0000, v0
	v_lshlrev_b32_e32 v0, 16, v1
	v_and_b32_e32 v1, 0xffff0000, v1
	s_waitcnt vmcnt(3)
	v_lshlrev_b32_e32 v10, 16, v36
	v_and_b32_e32 v11, 0xffff0000, v36
	v_lshlrev_b32_e32 v12, 16, v37
	v_and_b32_e32 v13, 0xffff0000, v37
	v_mul_f32_e32 v16, 0xbfb8aa3b, v10
	v_mul_f32_e32 v17, 0xbfb8aa3b, v11
	v_mul_f32_e32 v18, 0xbfb8aa3b, v12
	v_mul_f32_e32 v19, 0xbfb8aa3b, v13
	v_exp_f32_e32 v16, v16
	v_exp_f32_e32 v17, v17
	v_exp_f32_e32 v18, v18
	v_exp_f32_e32 v19, v19
	v_lshlrev_b32_e32 v14, 16, v38
	v_and_b32_e32 v15, 0xffff0000, v38
	v_add_f32_e32 v16, 1.0, v16
	v_add_f32_e32 v17, 1.0, v17
	v_add_f32_e32 v18, 1.0, v18
	v_add_f32_e32 v19, 1.0, v19
	v_mul_f32_e32 v20, 0xbfb8aa3b, v14
	v_mul_f32_e32 v21, 0xbfb8aa3b, v15
	v_rcp_f32_e32 v16, v16
	v_rcp_f32_e32 v17, v17
	v_rcp_f32_e32 v18, v18
	v_rcp_f32_e32 v19, v19
	v_exp_f32_e32 v20, v20
	v_exp_f32_e32 v21, v21
	v_pk_mul_f32 v[10:11], v[16:17], v[10:11]
	v_pk_mul_f32 v[12:13], v[18:19], v[12:13]
	v_add_f32_e32 v20, 1.0, v20
	v_pk_mul_f32 v[8:9], v[10:11], v[8:9]
	v_pk_mul_f32 v[10:11], v[12:13], v[0:1]
	v_add_f32_e32 v1, 1.0, v21
	v_rcp_f32_e32 v20, v20
	v_rcp_f32_e32 v21, v1
	v_lshlrev_b32_e32 v12, 16, v39
	v_cvt_pk_bf16_f32 v0, v8, v9
	v_lshlrev_b32_e32 v8, 16, v2
	v_and_b32_e32 v9, 0xffff0000, v2
	v_and_b32_e32 v13, 0xffff0000, v39
	v_mul_f32_e32 v2, 0xbfb8aa3b, v12
	v_cvt_pk_bf16_f32 v1, v10, v11
	v_pk_mul_f32 v[10:11], v[20:21], v[14:15]
	v_exp_f32_e32 v2, v2
	v_mul_f32_e32 v14, 0xbfb8aa3b, v13
	v_exp_f32_e32 v14, v14
	v_pk_mul_f32 v[8:9], v[10:11], v[8:9]
	v_add_f32_e32 v2, 1.0, v2
	v_rcp_f32_e32 v10, v2
	v_add_f32_e32 v2, 1.0, v14
	v_rcp_f32_e32 v11, v2
	v_cvt_pk_bf16_f32 v2, v8, v9
	v_lshlrev_b32_e32 v8, 16, v3
	v_and_b32_e32 v9, 0xffff0000, v3
	v_pk_mul_f32 v[10:11], v[10:11], v[12:13]
	s_waitcnt lgkmcnt(0)
; DI unsigned pack2(float a, float b) { f32x2_t v = {a, b}; bf16x2_t r = __builtin_convertvector(v, bf16x2_t); return __builtin_bit_cast(unsigned, r); }
; DI float bflo(unsigned u) { return __uint_as_float(u << 16); }
; DI float bfhi(unsigned u) { return __uint_as_float(u & 0xffff0000u); }
; DI float siluf_(float x) { return x * __builtin_amdgcn_rcpf(1.f + __expf(-x)); }
; DI void attn_write_staged(const f32x16& o0, const f32x16& o1, bf16_t* og, const bf16_t* z, size_t tok0, int head, int lane, bf16_t* wl) {
;     ...
; #pragma unroll
;   for (int k = 0; k < 4; ++k) {
;     const int ci = lane + 64 * k, row = ci >> 3, c8 = ci & 7;
;     const u32x4 ov = *(const u32x4*)(wl + row * 72 + c8 * 8);
;     const size_t off = (tok0 + row) * 1024 + head * 64 + c8 * 8;
;     const u32x4 zv = ldg16(z + off);
;     u32x4 r;
;     r.x = pack2(bflo(ov.x) * siluf_(bflo(zv.x)), bfhi(ov.x) * siluf_(bfhi(zv.x)));
;     r.y = pack2(bflo(ov.y) * siluf_(bflo(zv.y)), bfhi(ov.y) * siluf_(bfhi(zv.y)));
;     r.z = pack2(bflo(ov.z) * siluf_(bflo(zv.z)), bfhi(ov.z) * siluf_(bfhi(zv.z)));
;     r.w = pack2(bflo(ov.w) * siluf_(bflo(zv.w)), bfhi(ov.w) * siluf_(bfhi(zv.w)));
;     *(u32x4*)(og + off) = r;
;   }
	v_lshlrev_b32_e32 v12, 16, v4
	v_pk_mul_f32 v[8:9], v[10:11], v[8:9]
	v_or_b32_e32 v10, v32, v136
	v_cvt_pk_bf16_f32 v3, v8, v9
	v_lshl_add_u64 v[8:9], s[94:95], 0, v[40:41]
	global_store_dwordx4 v[8:9], v[0:3], off
	v_mov_b32_e32 v11, v33
	v_and_b32_e32 v13, 0xffff0000, v4
	v_or_b32_e32 v0, v32, v134
	v_mov_b32_e32 v1, v33
	v_lshlrev_b64 v[8:9], 11, v[0:1]
	v_or_b32_e32 v8, v8, v35
	v_lshl_add_u64 v[0:1], s[36:37], 0, v[8:9]
	v_lshlrev_b32_e32 v4, 16, v5
	v_and_b32_e32 v5, 0xffff0000, v5
	v_lshlrev_b32_e32 v14, 16, v6
	v_and_b32_e32 v15, 0xffff0000, v6
	v_lshlrev_b32_e32 v6, 16, v7
	v_and_b32_e32 v7, 0xffff0000, v7
	v_lshlrev_b64 v[10:11], 11, v[10:11]
	v_lshl_add_u64 v[8:9], s[94:95], 0, v[8:9]
	v_or_b32_e32 v10, v10, v35
	v_or_b32_e32 v32, v32, v138
	s_waitcnt vmcnt(3)
	v_mov_b32_e32 v0, v96
	v_mov_b32_e32 v1, v97
	v_mov_b32_e32 v2, v98
	v_mov_b32_e32 v3, v99
	v_lshlrev_b32_e32 v16, 16, v0
	v_and_b32_e32 v17, 0xffff0000, v0
	v_lshlrev_b32_e32 v0, 16, v1
	v_and_b32_e32 v1, 0xffff0000, v1
	v_lshlrev_b32_e32 v18, 16, v2
	v_and_b32_e32 v19, 0xffff0000, v2
	v_lshlrev_b32_e32 v2, 16, v3
	v_and_b32_e32 v3, 0xffff0000, v3
	v_mul_f32_e32 v20, 0xbfb8aa3b, v16
	v_mul_f32_e32 v21, 0xbfb8aa3b, v17
	v_mul_f32_e32 v22, 0xbfb8aa3b, v0
	v_mul_f32_e32 v23, 0xbfb8aa3b, v1
	v_mul_f32_e32 v24, 0xbfb8aa3b, v18
	v_mul_f32_e32 v25, 0xbfb8aa3b, v19
	v_mul_f32_e32 v26, 0xbfb8aa3b, v2
	v_mul_f32_e32 v27, 0xbfb8aa3b, v3
	v_exp_f32_e32 v20, v20
	v_exp_f32_e32 v21, v21
	v_exp_f32_e32 v22, v22
	v_exp_f32_e32 v23, v23
	v_exp_f32_e32 v24, v24
	v_exp_f32_e32 v25, v25
	v_exp_f32_e32 v26, v26
	v_exp_f32_e32 v27, v27
	v_add_f32_e32 v20, 1.0, v20
	v_add_f32_e32 v21, 1.0, v21
	v_add_f32_e32 v22, 1.0, v22
	v_add_f32_e32 v23, 1.0, v23
	v_add_f32_e32 v24, 1.0, v24
	v_add_f32_e32 v25, 1.0, v25
	v_add_f32_e32 v26, 1.0, v26
	v_add_f32_e32 v27, 1.0, v27
	v_rcp_f32_e32 v20, v20
	v_rcp_f32_e32 v21, v21
	v_rcp_f32_e32 v22, v22
	v_rcp_f32_e32 v23, v23
	v_rcp_f32_e32 v24, v24
	v_rcp_f32_e32 v25, v25
	v_rcp_f32_e32 v26, v26
	v_rcp_f32_e32 v27, v27
	v_pk_mul_f32 v[16:17], v[20:21], v[16:17]
	v_pk_mul_f32 v[0:1], v[22:23], v[0:1]
	v_pk_mul_f32 v[18:19], v[24:25], v[18:19]
	v_pk_mul_f32 v[2:3], v[26:27], v[2:3]
	v_pk_mul_f32 v[12:13], v[16:17], v[12:13]
	v_pk_mul_f32 v[4:5], v[0:1], v[4:5]
	v_pk_mul_f32 v[14:15], v[18:19], v[14:15]
	v_pk_mul_f32 v[6:7], v[2:3], v[6:7]
	v_cvt_pk_bf16_f32 v0, v12, v13
	v_cvt_pk_bf16_f32 v1, v4, v5
	v_cvt_pk_bf16_f32 v2, v14, v15
	v_cvt_pk_bf16_f32 v3, v6, v7
	global_store_dwordx4 v[8:9], v[0:3], off
	v_lshlrev_b64 v[12:13], 11, v[32:33]
	ds_read_b128 v[4:7], v167 offset:43264
	v_lshl_add_u64 v[0:1], s[36:37], 0, v[10:11]
	v_lshl_add_u64 v[14:15], s[94:95], 0, v[10:11]
	ds_read_b128 v[8:11], v167 offset:44416
	s_waitcnt lgkmcnt(1)
	v_lshlrev_b32_e32 v18, 16, v4
	v_and_b32_e32 v19, 0xffff0000, v4
	v_lshlrev_b32_e32 v4, 16, v5
	v_and_b32_e32 v5, 0xffff0000, v5
	v_lshlrev_b32_e32 v20, 16, v6
	v_and_b32_e32 v21, 0xffff0000, v6
	v_lshlrev_b32_e32 v6, 16, v7
	v_and_b32_e32 v7, 0xffff0000, v7
	v_or_b32_e32 v12, v12, v35
	v_lshl_add_u64 v[16:17], s[36:37], 0, v[12:13]
	s_waitcnt vmcnt(3)
	v_mov_b32_e32 v0, v100
	v_mov_b32_e32 v1, v101
	v_mov_b32_e32 v2, v102
	v_mov_b32_e32 v3, v103
	v_lshlrev_b32_e32 v22, 16, v0
	v_and_b32_e32 v23, 0xffff0000, v0
	v_lshlrev_b32_e32 v0, 16, v1
	v_and_b32_e32 v1, 0xffff0000, v1
	v_lshlrev_b32_e32 v24, 16, v2
	v_and_b32_e32 v25, 0xffff0000, v2
	v_lshlrev_b32_e32 v2, 16, v3
	v_and_b32_e32 v3, 0xffff0000, v3
	v_mul_f32_e32 v26, 0xbfb8aa3b, v22
	v_mul_f32_e32 v27, 0xbfb8aa3b, v23
	v_mul_f32_e32 v28, 0xbfb8aa3b, v0
	v_mul_f32_e32 v29, 0xbfb8aa3b, v1
	v_mul_f32_e32 v30, 0xbfb8aa3b, v24
	v_mul_f32_e32 v31, 0xbfb8aa3b, v25
	v_mul_f32_e32 v32, 0xbfb8aa3b, v2
	v_mul_f32_e32 v33, 0xbfb8aa3b, v3
	v_exp_f32_e32 v26, v26
	v_exp_f32_e32 v27, v27
	v_exp_f32_e32 v28, v28
	v_exp_f32_e32 v29, v29
	v_exp_f32_e32 v30, v30
	v_exp_f32_e32 v31, v31
	v_exp_f32_e32 v32, v32
	v_exp_f32_e32 v33, v33
	v_add_f32_e32 v26, 1.0, v26
	v_add_f32_e32 v27, 1.0, v27
	v_add_f32_e32 v28, 1.0, v28
	v_add_f32_e32 v29, 1.0, v29
	v_add_f32_e32 v30, 1.0, v30
	v_add_f32_e32 v31, 1.0, v31
	v_add_f32_e32 v32, 1.0, v32
	v_add_f32_e32 v33, 1.0, v33
	v_rcp_f32_e32 v26, v26
	v_rcp_f32_e32 v27, v27
	v_rcp_f32_e32 v28, v28
	v_rcp_f32_e32 v29, v29
	v_rcp_f32_e32 v30, v30
	v_rcp_f32_e32 v31, v31
	v_rcp_f32_e32 v32, v32
	v_rcp_f32_e32 v33, v33
	v_pk_mul_f32 v[22:23], v[26:27], v[22:23]
	v_pk_mul_f32 v[0:1], v[28:29], v[0:1]
	v_pk_mul_f32 v[24:25], v[30:31], v[24:25]
	v_pk_mul_f32 v[2:3], v[32:33], v[2:3]
	v_pk_mul_f32 v[18:19], v[22:23], v[18:19]
	v_pk_mul_f32 v[4:5], v[0:1], v[4:5]
	v_pk_mul_f32 v[20:21], v[24:25], v[20:21]
	v_pk_mul_f32 v[6:7], v[2:3], v[6:7]
	v_cvt_pk_bf16_f32 v0, v18, v19
	v_cvt_pk_bf16_f32 v1, v4, v5
	v_cvt_pk_bf16_f32 v2, v20, v21
	v_cvt_pk_bf16_f32 v3, v6, v7
	global_store_dwordx4 v[14:15], v[0:3], off
	v_lshl_add_u64 v[4:5], s[94:95], 0, v[12:13]
	s_waitcnt lgkmcnt(0)
	v_lshlrev_b32_e32 v6, 16, v8
	v_and_b32_e32 v7, 0xffff0000, v8
	v_lshlrev_b32_e32 v8, 16, v9
	v_and_b32_e32 v9, 0xffff0000, v9
	v_lshlrev_b32_e32 v12, 16, v10
	v_and_b32_e32 v13, 0xffff0000, v10
	v_lshlrev_b32_e32 v10, 16, v11
	v_and_b32_e32 v11, 0xffff0000, v11
	s_waitcnt vmcnt(3)
	v_mov_b32_e32 v0, v104
	v_mov_b32_e32 v1, v105
	v_mov_b32_e32 v2, v106
	v_mov_b32_e32 v3, v107
	v_lshlrev_b32_e32 v14, 16, v0
	v_and_b32_e32 v15, 0xffff0000, v0
	v_lshlrev_b32_e32 v0, 16, v1
	v_and_b32_e32 v1, 0xffff0000, v1
	v_lshlrev_b32_e32 v16, 16, v2
	v_and_b32_e32 v17, 0xffff0000, v2
	v_lshlrev_b32_e32 v2, 16, v3
	v_and_b32_e32 v3, 0xffff0000, v3
	v_mul_f32_e32 v18, 0xbfb8aa3b, v14
	v_mul_f32_e32 v19, 0xbfb8aa3b, v15
	v_mul_f32_e32 v20, 0xbfb8aa3b, v0
	v_mul_f32_e32 v21, 0xbfb8aa3b, v1
	v_mul_f32_e32 v22, 0xbfb8aa3b, v16
	v_mul_f32_e32 v23, 0xbfb8aa3b, v17
	v_mul_f32_e32 v24, 0xbfb8aa3b, v2
	v_mul_f32_e32 v25, 0xbfb8aa3b, v3
	v_exp_f32_e32 v18, v18
	v_exp_f32_e32 v19, v19
	v_exp_f32_e32 v20, v20
	v_exp_f32_e32 v21, v21
	v_exp_f32_e32 v22, v22
	v_exp_f32_e32 v23, v23
	v_exp_f32_e32 v24, v24
	v_exp_f32_e32 v25, v25
	v_add_f32_e32 v18, 1.0, v18
	v_add_f32_e32 v19, 1.0, v19
	v_add_f32_e32 v20, 1.0, v20
	v_add_f32_e32 v21, 1.0, v21
	v_add_f32_e32 v22, 1.0, v22
	v_add_f32_e32 v23, 1.0, v23
	v_add_f32_e32 v24, 1.0, v24
	v_add_f32_e32 v25, 1.0, v25
	v_rcp_f32_e32 v18, v18
	v_rcp_f32_e32 v19, v19
	v_rcp_f32_e32 v20, v20
	v_rcp_f32_e32 v21, v21
	v_rcp_f32_e32 v22, v22
	v_rcp_f32_e32 v23, v23
	v_rcp_f32_e32 v24, v24
	v_rcp_f32_e32 v25, v25
	v_pk_mul_f32 v[14:15], v[18:19], v[14:15]
	v_pk_mul_f32 v[0:1], v[20:21], v[0:1]
	v_pk_mul_f32 v[16:17], v[22:23], v[16:17]
	v_pk_mul_f32 v[2:3], v[24:25], v[2:3]
	v_pk_mul_f32 v[6:7], v[14:15], v[6:7]
	v_pk_mul_f32 v[8:9], v[0:1], v[8:9]
	v_pk_mul_f32 v[12:13], v[16:17], v[12:13]
	v_pk_mul_f32 v[10:11], v[2:3], v[10:11]
	v_cvt_pk_bf16_f32 v0, v6, v7
	v_cvt_pk_bf16_f32 v1, v8, v9
	v_cvt_pk_bf16_f32 v2, v12, v13
	v_cvt_pk_bf16_f32 v3, v10, v11
	global_store_dwordx4 v[4:5], v[0:3], off
	s_cbranch_scc1 .LBB0_352

; DI void phase_attn_swa(const Params& P, const float* sinks, bf16_t* og, unsigned char* smem, int L, int G) {
;     ...
;     float m = sinks[head] * LOG2E, l = 1.f;
;     const bf16_t* kb = big + SW_K + (size_t)b * SEQ * 256 + g * 64;
;     const bf16_t* vb = big + SW_VT + (size_t)((b * 4 + g) * 64) * SEQ;
;     const int jlo = (t0 - 127 > 0 ? t0 - 127 : 0) >> 6, jhi = (t0 + 31) >> 6;
;     KVR R; kv64_fetch(R, kb, 256, vb, SEQ, jlo * 64, true, tid);
;     __syncthreads();
;     kv64_store(R, sK, sVt, tid);
;     if (jlo < jhi) kv64_fetch(R, kb, 256, vb, SEQ, jlo * 64 + 64, true, tid);
.LBB0_344:
	s_cmp_gt_u32 s46, s41
	s_cbranch_scc1 .LBB0_336
	v_cmp_lt_i32_e32 vcc, v169, v170
	v_lshl_add_u64 v[152:153], v[0:1], 0, v[142:143]
	v_lshl_add_u64 v[154:155], v[2:3], 0, v[142:143]
	v_cndmask_b32_e32 v0, v168, v169, vcc
	v_lshlrev_b32_e32 v174, 2, v0
	v_mov_b32_e32 v0, 0
	v_lshl_add_u64 v[156:157], v[4:5], 0, v[142:143]
	v_mul_f32_e32 v176, 0x3fb8aa3b, v10
	v_add_u32_e32 v151, 0xffffff80, v150
	s_mov_b32 s47, 0
	s_lshl_b32 s38, s46, 6
	v_mov_b32_e32 v175, 0.5
	v_mov_b32_e32 v1, v0
	v_mov_b32_e32 v2, v0
	v_mov_b32_e32 v3, v0
	v_mov_b32_e32 v4, v0
	v_mov_b32_e32 v5, v0
	v_mov_b32_e32 v6, v0
	v_mov_b32_e32 v7, v0
	v_mov_b32_e32 v8, v0
	v_mov_b32_e32 v9, v0
	v_mov_b32_e32 v10, v0
	v_mov_b32_e32 v11, v0
	v_mov_b32_e32 v12, v0
	v_mov_b32_e32 v13, v0
	v_mov_b32_e32 v14, v0
	v_mov_b32_e32 v15, v0
	v_mov_b32_e32 v16, v0
	v_mov_b32_e32 v17, v0
	v_mov_b32_e32 v18, v0
	v_mov_b32_e32 v19, v0
	v_mov_b32_e32 v20, v0
	v_mov_b32_e32 v21, v0
	v_mov_b32_e32 v22, v0
	v_mov_b32_e32 v23, v0
	v_mov_b32_e32 v24, v0
	v_mov_b32_e32 v25, v0
	v_mov_b32_e32 v26, v0
	v_mov_b32_e32 v27, v0
	v_mov_b32_e32 v28, v0
	v_mov_b32_e32 v29, v0
	v_mov_b32_e32 v30, v0
	v_mov_b32_e32 v31, v0

; #define MFMA(a, b, c) __builtin_amdgcn_mfma_f32_32x32x16_bf16((a), (b), (c), 0, 0, 0)
; template <int DQK, bool MASKED, int MODE, class MF>
; DI void attn_step(const bf16_t* sK, const bf16_t* sVt, const bf16x8 (&qf)[DQK / 16], f32x16& o0, f32x16& o1, float& m, float& l,
;                   float sc, const MF& mf, int lane, f32x16 (&s)[2], float invl, bool lanevalid = true) {
;     ...
;   bf16x8 kf[2][DQK / 16];
; #pragma unroll
;   for (int sub = 0; sub < 2; ++sub)
; #pragma unroll
;     for (int ks = 0; ks < DQK / 16; ++ks) kf[sub][ks] = *(const bf16x8*)(sK + (sub * 32 + pr) * KST + ks * 16 + 8 * h);
;   __builtin_amdgcn_sched_barrier(0);
; #pragma unroll
;   for (int q = 0; q < 16; ++q) { s[0][q] = 0.f; s[1][q] = 0.f; }
; #pragma unroll
;   for (int ks = 0; ks < DQK / 16; ++ks) {
;     s[0] = MFMA(kf[0][ks], qf[ks], s[0]);
;     s[1] = MFMA(kf[1][ks], qf[ks], s[1]);
;   }
;   bf16x8 vf[2][2][2];
;   if (MODE != 1) {
; #pragma unroll
;     for (int sub = 0; sub < 2; ++sub)
; #pragma unroll
;       for (int s2 = 0; s2 < 2; ++s2) {
;         vf[sub][s2][0] = *(const bf16x8*)(sVt + r * 72 + sub * 32 + s2 * 16 + 8 * h);
;         vf[sub][s2][1] = *(const bf16x8*)(sVt + (32 + r) * 72 + sub * 32 + s2 * 16 + 8 * h);
;       }
;     __builtin_amdgcn_sched_barrier(0);
;   }
;   float mxr = -3.0e38f;
; #pragma unroll
;   for (int sub = 0; sub < 2; ++sub)
; #pragma unroll
;     for (int q = 0; q < 16; ++q) {
;       if (MASKED) { const int kk = sub * 32 + 16 * (q >> 3) + 8 * h + (q & 7); s[sub][q] = mf(kk) ? s[sub][q] : -3.0e38f; }
;       if (MODE != 2) mxr = fmaxf(mxr, s[sub][q]);
;     }
.LBB0_350:
	s_mulk_i32 s0, 0x4800
	v_add_u32_e32 v40, s0, v163
	ds_read_b128 v[32:35], v40
	ds_read_b128 v[96:99], v40 offset:32
	ds_read_b128 v[100:103], v40 offset:64
	ds_read_b128 v[104:107], v40 offset:96
	ds_read_b128 v[36:39], v40 offset:4608
	ds_read_b128 v[108:111], v40 offset:4640
	ds_read_b128 v[112:115], v40 offset:4672
	ds_read_b128 v[178:181], v40 offset:4704
	v_add_u32_e32 v116, s0, v137
	s_waitcnt lgkmcnt(7)
	v_mfma_f32_32x32x16_bf16 v[48:63], v[32:35], v[64:67], 0
	s_waitcnt lgkmcnt(3)
	v_mfma_f32_32x32x16_bf16 v[32:47], v[36:39], v[64:67], 0
	v_mfma_f32_32x32x16_bf16 v[48:63], v[96:99], v[68:71], v[48:63]
	v_add3_u32 v96, v116, v164, v171
	v_add3_u32 v97, v116, v165, v171
	s_waitcnt lgkmcnt(2)
	v_mfma_f32_32x32x16_bf16 v[32:47], v[108:111], v[68:71], v[32:47]
	v_mfma_f32_32x32x16_bf16 v[48:63], v[100:103], v[72:75], v[48:63]
	s_waitcnt lgkmcnt(1)
	v_mfma_f32_32x32x16_bf16 v[32:47], v[112:115], v[72:75], v[32:47]
	v_mfma_f32_32x32x16_bf16 v[48:63], v[104:107], v[76:79], v[48:63]
	ds_read_b128 v[124:127], v96 offset:9216
	ds_read_b128 v[116:119], v96 offset:9248
	ds_read_b128 v[120:123], v97 offset:9216
	ds_read_b128 v[112:115], v97 offset:9248
	ds_read_b128 v[108:111], v96 offset:9280
	ds_read_b128 v[100:103], v96 offset:9312
	ds_read_b128 v[104:107], v97 offset:9280
	ds_read_b128 v[96:99], v97 offset:9312
	s_waitcnt lgkmcnt(8)
	v_mfma_f32_32x32x16_bf16 v[32:47], v[178:181], v[76:79], v[32:47]
	v_add_u32_e32 v128, s38, v162
	v_cmp_le_u32_e32 vcc, v128, v150
	v_cmp_gt_i32_e64 s[0:1], v128, v151
	s_and_b64 vcc, vcc, s[0:1]
	v_cndmask_b32_e32 v48, v172, v48, vcc
	v_cmp_lt_u32_e32 vcc, v128, v150
	v_cmp_ge_i32_e64 s[0:1], v128, v151
	s_and_b64 vcc, vcc, s[0:1]
	v_add_u32_e32 v177, 2, v128
	v_cndmask_b32_e32 v49, v172, v49, vcc
	v_cmp_le_u32_e32 vcc, v177, v150
	v_cmp_gt_i32_e64 s[0:1], v177, v151
	s_and_b64 vcc, vcc, s[0:1]
	v_add_u32_e32 v177, 3, v128
	v_cndmask_b32_e32 v50, v172, v50, vcc
	v_cmp_le_u32_e32 vcc, v177, v150
	v_cmp_gt_i32_e64 s[0:1], v177, v151
	s_and_b64 vcc, vcc, s[0:1]
	v_add_u32_e32 v177, 4, v128
	v_cndmask_b32_e32 v51, v172, v51, vcc
	v_cmp_le_u32_e32 vcc, v177, v150
	v_cmp_gt_i32_e64 s[0:1], v177, v151
	s_and_b64 vcc, vcc, s[0:1]
	v_add_u32_e32 v177, 5, v128
	v_cndmask_b32_e32 v52, v172, v52, vcc
	v_cmp_le_u32_e32 vcc, v177, v150
	v_cmp_gt_i32_e64 s[0:1], v177, v151
	s_and_b64 vcc, vcc, s[0:1]
	v_add_u32_e32 v177, 6, v128
	v_cndmask_b32_e32 v53, v172, v53, vcc
	v_cmp_le_u32_e32 vcc, v177, v150
	v_cmp_gt_i32_e64 s[0:1], v177, v151
	v_add_u32_e32 v177, s38, v161
	s_and_b64 vcc, vcc, s[0:1]
	v_or_b32_e32 v178, 7, v177
	v_cndmask_b32_e32 v54, v172, v54, vcc
	v_cmp_le_u32_e32 vcc, v178, v150
	v_cmp_gt_i32_e64 s[0:1], v178, v151
	s_and_b64 vcc, vcc, s[0:1]
	v_add_u32_e32 v178, 16, v128
	v_cndmask_b32_e32 v55, v172, v55, vcc
	v_cmp_le_u32_e32 vcc, v178, v150
	v_cmp_gt_i32_e64 s[0:1], v178, v151
	s_and_b64 vcc, vcc, s[0:1]
	v_add_u32_e32 v178, 17, v128
	v_cndmask_b32_e32 v56, v172, v56, vcc
	v_cmp_le_u32_e32 vcc, v178, v150
	v_cmp_gt_i32_e64 s[0:1], v178, v151
	s_and_b64 vcc, vcc, s[0:1]
	v_add_u32_e32 v178, 18, v128
	v_cndmask_b32_e32 v57, v172, v57, vcc
	v_cmp_le_u32_e32 vcc, v178, v150
	v_cmp_gt_i32_e64 s[0:1], v178, v151
	s_and_b64 vcc, vcc, s[0:1]
	v_add_u32_e32 v178, 19, v128
	v_cndmask_b32_e32 v58, v172, v58, vcc
	v_cmp_le_u32_e32 vcc, v178, v150
	v_cmp_gt_i32_e64 s[0:1], v178, v151
	s_and_b64 vcc, vcc, s[0:1]
	v_add_u32_e32 v178, 20, v128
	v_cndmask_b32_e32 v59, v172, v59, vcc
	v_cmp_le_u32_e32 vcc, v178, v150
	v_cmp_gt_i32_e64 s[0:1], v178, v151
	s_and_b64 vcc, vcc, s[0:1]
	v_add_u32_e32 v178, 21, v128
	v_cndmask_b32_e32 v60, v172, v60, vcc
	v_cmp_le_u32_e32 vcc, v178, v150
	v_cmp_gt_i32_e64 s[0:1], v178, v151
	s_and_b64 vcc, vcc, s[0:1]
	v_add_u32_e32 v178, 22, v128
	v_cndmask_b32_e32 v61, v172, v61, vcc
	v_cmp_le_u32_e32 vcc, v178, v150
	v_cmp_gt_i32_e64 s[0:1], v178, v151
	s_and_b64 vcc, vcc, s[0:1]
	v_or_b32_e32 v178, 23, v177
	v_cndmask_b32_e32 v62, v172, v62, vcc
	v_cmp_le_u32_e32 vcc, v178, v150
	v_cmp_gt_i32_e64 s[0:1], v178, v151
	s_and_b64 vcc, vcc, s[0:1]
	v_add_u32_e32 v178, 32, v128
	v_cndmask_b32_e32 v63, v172, v63, vcc
	v_cmp_le_u32_e32 vcc, v178, v150
	v_cmp_gt_i32_e64 s[0:1], v178, v151
	s_and_b64 vcc, vcc, s[0:1]
	v_cndmask_b32_e32 v178, v172, v32, vcc
	v_add_u32_e32 v32, 33, v128
	v_cmp_le_u32_e32 vcc, v32, v150
	v_cmp_gt_i32_e64 s[0:1], v32, v151
	s_and_b64 vcc, vcc, s[0:1]
	v_add_u32_e32 v32, 34, v128
	v_cndmask_b32_e32 v33, v172, v33, vcc
	v_cmp_le_u32_e32 vcc, v32, v150
	v_cmp_gt_i32_e64 s[0:1], v32, v151
	s_and_b64 vcc, vcc, s[0:1]
	v_add_u32_e32 v32, 35, v128
	v_cndmask_b32_e32 v34, v172, v34, vcc
	v_cmp_le_u32_e32 vcc, v32, v150
	v_cmp_gt_i32_e64 s[0:1], v32, v151
	s_and_b64 vcc, vcc, s[0:1]
	v_add_u32_e32 v32, 36, v128
	v_cndmask_b32_e32 v35, v172, v35, vcc
	v_cmp_le_u32_e32 vcc, v32, v150
	v_cmp_gt_i32_e64 s[0:1], v32, v151
	s_and_b64 vcc, vcc, s[0:1]
	v_add_u32_e32 v32, 37, v128
	v_cndmask_b32_e32 v36, v172, v36, vcc
	v_cmp_le_u32_e32 vcc, v32, v150
	v_cmp_gt_i32_e64 s[0:1], v32, v151
	s_and_b64 vcc, vcc, s[0:1]
	v_add_u32_e32 v32, 38, v128
	v_cndmask_b32_e32 v37, v172, v37, vcc
	v_cmp_le_u32_e32 vcc, v32, v150
	v_cmp_gt_i32_e64 s[0:1], v32, v151
	s_and_b64 vcc, vcc, s[0:1]
	v_or_b32_e32 v32, 39, v177
	v_cndmask_b32_e32 v38, v172, v38, vcc
	v_cmp_le_u32_e32 vcc, v32, v150
	v_cmp_gt_i32_e64 s[0:1], v32, v151
	s_and_b64 vcc, vcc, s[0:1]
	v_add_u32_e32 v32, 48, v128
	v_cndmask_b32_e32 v39, v172, v39, vcc
	v_cmp_le_u32_e32 vcc, v32, v150
	v_cmp_gt_i32_e64 s[0:1], v32, v151
	s_and_b64 vcc, vcc, s[0:1]
	v_add_u32_e32 v32, 49, v128
	v_cndmask_b32_e32 v179, v172, v40, vcc
; #define MFMA(a, b, c) __builtin_amdgcn_mfma_f32_32x32x16_bf16((a), (b), (c), 0, 0, 0)
; DI unsigned pack2(float a, float b) { f32x2_t v = {a, b}; bf16x2_t r = __builtin_convertvector(v, bf16x2_t); return __builtin_bit_cast(unsigned, r); }
; DI float fexp2(float x) { return __builtin_amdgcn_exp2f(x); }
; DI float shx(float v, int m) { return __shfl_xor(v, m, 64); }
; template <int DQK, bool MASKED, int MODE, class MF>
; DI void attn_step(const bf16_t* sK, const bf16_t* sVt, const bf16x8 (&qf)[DQK / 16], f32x16& o0, f32x16& o1, float& m, float& l,
;                   float sc, const MF& mf, int lane, f32x16 (&s)[2], float invl, bool lanevalid = true) {
;     ...
;   float mxr = -3.0e38f;
; #pragma unroll
;   for (int sub = 0; sub < 2; ++sub)
; #pragma unroll
;     for (int q = 0; q < 16; ++q) {
;       if (MASKED) { const int kk = sub * 32 + 16 * (q >> 3) + 8 * h + (q & 7); s[sub][q] = mf(kk) ? s[sub][q] : -3.0e38f; }
;       if (MODE != 2) mxr = fmaxf(mxr, s[sub][q]);
;     }
;   float alpha = 1.f;
;   if (MODE != 2) {
;     float mx = fmaxf(m, mxr * sc);
;     mx = fmaxf(mx, shx(mx, 32));
;     if (!MASKED) mx = lanevalid ? mx : m;
;     alpha = fexp2(m - mx);
;     m = mx;
;   }
;   const float moff = (!MASKED && !lanevalid) ? 1.0e30f : m;
;   float ps = 0.f;
; #pragma unroll
;   for (int sub = 0; sub < 2; ++sub)
; #pragma unroll
;     for (int q = 0; q < 16; ++q) {
;       float pv = fexp2(__builtin_fmaf(s[sub][q], sc, -moff));
;       if (MASKED && MODE != 0) pv = (s[sub][q] > -1.0e38f) ? pv : 0.f;
;       if (MODE == 2) pv *= invl;
;       s[sub][q] = pv;
;       ps += pv;
;     }
;   if (MODE != 2) {
;     ps += shx(ps, 32);
;     l = l * alpha + ps;
;   }
;   if (MODE == 1) return;
;   if (MODE == 0) {
; #pragma unroll
;     for (int q = 0; q < 16; ++q) { o0[q] *= alpha; o1[q] *= alpha; }
;   }
; #pragma unroll
;   for (int sub = 0; sub < 2; ++sub)
; #pragma unroll
;     for (int s2 = 0; s2 < 2; ++s2) {
;       union { bf16x8 v; unsigned u[4]; } pb;
; #pragma unroll
;       for (int e = 0; e < 4; ++e) pb.u[e] = pack2(s[sub][8 * s2 + 2 * e], s[sub][8 * s2 + 2 * e + 1]);
;       o0 = MFMA(vf[sub][s2][0], pb.v, o0);
;       o1 = MFMA(vf[sub][s2][1], pb.v, o1);
;     }
	v_cmp_le_u32_e32 vcc, v32, v150
	v_cmp_gt_i32_e64 s[0:1], v32, v151
	s_and_b64 vcc, vcc, s[0:1]
	v_add_u32_e32 v32, 50, v128
	v_cndmask_b32_e32 v41, v172, v41, vcc
	v_cmp_le_u32_e32 vcc, v32, v150
	v_cmp_gt_i32_e64 s[0:1], v32, v151
	s_and_b64 vcc, vcc, s[0:1]
	v_add_u32_e32 v32, 51, v128
	v_cndmask_b32_e32 v42, v172, v42, vcc
	v_cmp_le_u32_e32 vcc, v32, v150
	v_cmp_gt_i32_e64 s[0:1], v32, v151
	s_and_b64 vcc, vcc, s[0:1]
	v_add_u32_e32 v32, 52, v128
	v_cndmask_b32_e32 v43, v172, v43, vcc
	v_cmp_le_u32_e32 vcc, v32, v150
	v_cmp_gt_i32_e64 s[0:1], v32, v151
	s_and_b64 vcc, vcc, s[0:1]
	v_add_u32_e32 v32, 53, v128
	v_cndmask_b32_e32 v44, v172, v44, vcc
	v_cmp_le_u32_e32 vcc, v32, v150
	v_cmp_gt_i32_e64 s[0:1], v32, v151
	s_and_b64 vcc, vcc, s[0:1]
	v_add_u32_e32 v32, 54, v128
	v_cndmask_b32_e32 v45, v172, v45, vcc
	v_cmp_le_u32_e32 vcc, v32, v150
	v_cmp_gt_i32_e64 s[0:1], v32, v151
	s_and_b64 vcc, vcc, s[0:1]
	v_or_b32_e32 v32, 55, v177
	v_cndmask_b32_e32 v46, v172, v46, vcc
	v_cmp_le_u32_e32 vcc, v32, v150
	v_cmp_gt_i32_e64 s[0:1], v32, v151
	v_max3_f32 v32, v48, s43, v49
	v_max3_f32 v32, v32, v50, v51
	v_max3_f32 v32, v32, v52, v53
	v_max3_f32 v32, v32, v54, v55
	v_max3_f32 v32, v32, v56, v57
	v_max3_f32 v32, v32, v58, v59
	v_max3_f32 v32, v32, v60, v61
	v_max3_f32 v32, v32, v62, v63
	v_max3_f32 v32, v32, v178, v33
	v_max3_f32 v32, v32, v34, v35
	v_max3_f32 v32, v32, v36, v37
	v_max3_f32 v32, v32, v38, v39
	v_max3_f32 v32, v32, v179, v41
	s_and_b64 vcc, vcc, s[0:1]
	v_max3_f32 v32, v32, v42, v43
	v_cndmask_b32_e32 v47, v172, v47, vcc
	v_max3_f32 v32, v32, v44, v45
	v_max3_f32 v32, v32, v46, v47
	v_mul_f32_e32 v32, 0x3e38aa3b, v32
	v_max_f32_e32 v40, v176, v176
	v_max_f32_e32 v32, v40, v32
	ds_bpermute_b32 v40, v174, v32
	s_add_i32 s47, s47, 1
	s_add_i32 s0, s46, s47
	s_add_i32 s38, s38, 64
	s_add_i32 s0, s0, -1
	s_waitcnt lgkmcnt(0)
	v_max_f32_e32 v40, v40, v40
	v_max_f32_e32 v32, v32, v40
	v_fma_f32 v40, v48, s44, -v32
	v_exp_f32_e32 v48, v40
	v_fma_f32 v49, v49, s44, -v32
	v_exp_f32_e32 v49, v49
	v_fma_f32 v50, v50, s44, -v32
	v_exp_f32_e32 v50, v50
	v_fma_f32 v51, v51, s44, -v32
	v_exp_f32_e32 v51, v51
	v_fma_f32 v52, v52, s44, -v32
	v_add_f32_e32 v128, 0, v48
	v_exp_f32_e32 v52, v52
	v_fma_f32 v53, v53, s44, -v32
	v_add_f32_e32 v128, v49, v128
	v_exp_f32_e32 v53, v53
	v_fma_f32 v54, v54, s44, -v32
	v_add_f32_e32 v128, v50, v128
	v_exp_f32_e32 v54, v54
	v_fma_f32 v55, v55, s44, -v32
	v_add_f32_e32 v128, v51, v128
	v_exp_f32_e32 v55, v55
	v_fma_f32 v56, v56, s44, -v32
	v_add_f32_e32 v128, v52, v128
	v_exp_f32_e32 v56, v56
	v_fma_f32 v57, v57, s44, -v32
	v_add_f32_e32 v128, v53, v128
	v_exp_f32_e32 v57, v57
	v_fma_f32 v58, v58, s44, -v32
	v_add_f32_e32 v128, v54, v128
	v_exp_f32_e32 v58, v58
	v_fma_f32 v59, v59, s44, -v32
	v_add_f32_e32 v128, v55, v128
	v_exp_f32_e32 v59, v59
	v_fma_f32 v60, v60, s44, -v32
	v_add_f32_e32 v128, v56, v128
	v_exp_f32_e32 v60, v60
	v_fma_f32 v61, v61, s44, -v32
	v_add_f32_e32 v128, v57, v128
	v_exp_f32_e32 v61, v61
	v_fma_f32 v62, v62, s44, -v32
	v_add_f32_e32 v128, v58, v128
	v_exp_f32_e32 v62, v62
	v_fma_f32 v63, v63, s44, -v32
	v_sub_f32_e32 v40, v176, v32
	v_add_f32_e32 v128, v59, v128
	v_exp_f32_e32 v63, v63
	v_fma_f32 v176, v178, s44, -v32
	v_add_f32_e32 v128, v60, v128
	v_exp_f32_e32 v176, v176
	v_fma_f32 v33, v33, s44, -v32
	v_add_f32_e32 v128, v61, v128
	v_exp_f32_e32 v33, v33
	v_fma_f32 v34, v34, s44, -v32
	v_add_f32_e32 v128, v62, v128
	v_exp_f32_e32 v177, v34
	v_fma_f32 v34, v35, s44, -v32
	v_add_f32_e32 v128, v63, v128
	v_exp_f32_e32 v178, v34
	v_fma_f32 v34, v36, s44, -v32
	v_add_f32_e32 v128, v176, v128
	v_exp_f32_e32 v180, v34
	v_fma_f32 v35, v37, s44, -v32
	v_add_f32_e32 v34, v33, v128
	v_exp_f32_e32 v128, v35
	v_fma_f32 v35, v38, s44, -v32
	v_add_f32_e32 v34, v177, v34
	v_exp_f32_e32 v38, v35
	v_fma_f32 v35, v39, s44, -v32
	v_add_f32_e32 v34, v178, v34
	v_exp_f32_e32 v39, v35
	v_add_f32_e32 v34, v180, v34
	v_exp_f32_e32 v40, v40
	v_add_f32_e32 v34, v128, v34
	v_add_f32_e32 v34, v38, v34
	v_add_f32_e32 v181, v39, v34
	v_fma_f32 v34, v179, s44, -v32
	v_exp_f32_e32 v179, v34
	v_pk_mul_f32 v[14:15], v[14:15], v[40:41] op_sel_hi:[1,0]
	v_pk_mul_f32 v[12:13], v[12:13], v[40:41] op_sel_hi:[1,0]
	v_pk_mul_f32 v[10:11], v[10:11], v[40:41] op_sel_hi:[1,0]
	v_pk_mul_f32 v[8:9], v[8:9], v[40:41] op_sel_hi:[1,0]
	v_pk_mul_f32 v[6:7], v[6:7], v[40:41] op_sel_hi:[1,0]
	v_pk_mul_f32 v[4:5], v[4:5], v[40:41] op_sel_hi:[1,0]
	v_pk_mul_f32 v[2:3], v[2:3], v[40:41] op_sel_hi:[1,0]
	v_pk_mul_f32 v[0:1], v[0:1], v[40:41] op_sel_hi:[1,0]
	v_pk_mul_f32 v[30:31], v[30:31], v[40:41] op_sel_hi:[1,0]
	v_cvt_pk_bf16_f32 v34, v48, v49
	v_cvt_pk_bf16_f32 v35, v50, v51
	v_cvt_pk_bf16_f32 v36, v52, v53
	v_cvt_pk_bf16_f32 v37, v54, v55
	v_pk_mul_f32 v[28:29], v[28:29], v[40:41] op_sel_hi:[1,0]
	v_pk_mul_f32 v[26:27], v[26:27], v[40:41] op_sel_hi:[1,0]
	v_pk_mul_f32 v[24:25], v[24:25], v[40:41] op_sel_hi:[1,0]
	v_pk_mul_f32 v[22:23], v[22:23], v[40:41] op_sel_hi:[1,0]
	v_pk_mul_f32 v[20:21], v[20:21], v[40:41] op_sel_hi:[1,0]
	v_pk_mul_f32 v[18:19], v[18:19], v[40:41] op_sel_hi:[1,0]
	v_pk_mul_f32 v[16:17], v[16:17], v[40:41] op_sel_hi:[1,0]
	v_mfma_f32_32x32x16_bf16 v[0:15], v[124:127], v[34:37], v[0:15]
	v_fma_f32 v42, v42, s44, -v32
	v_exp_f32_e32 v42, v42
	v_fma_f32 v43, v43, s44, -v32
	v_exp_f32_e32 v43, v43
	v_fma_f32 v44, v44, s44, -v32
	v_add_f32_e32 v48, v179, v181
	v_exp_f32_e32 v44, v44
	v_mfma_f32_32x32x16_bf16 v[16:31], v[120:123], v[34:37], v[16:31]
	v_fma_f32 v34, v41, s44, -v32
	v_exp_f32_e32 v41, v34
	v_cvt_pk_bf16_f32 v34, v56, v57
	v_cvt_pk_bf16_f32 v35, v58, v59
	v_cvt_pk_bf16_f32 v36, v60, v61
	v_cvt_pk_bf16_f32 v37, v62, v63
	v_add_f32_e32 v48, v41, v48
	s_cmp_ge_u32 s0, s41
	v_mfma_f32_32x32x16_bf16 v[0:15], v[116:119], v[34:37], v[0:15]
	v_mfma_f32_32x32x16_bf16 v[16:31], v[112:115], v[34:37], v[16:31]
	v_add_f32_e32 v34, v42, v48
	v_add_f32_e32 v34, v43, v34
	v_add_f32_e32 v48, v44, v34
	v_cvt_pk_bf16_f32 v34, v176, v33
	v_cvt_pk_bf16_f32 v35, v177, v178
	v_cvt_pk_bf16_f32 v36, v180, v128
	v_cvt_pk_bf16_f32 v37, v38, v39
	v_fma_f32 v33, v45, s44, -v32
	v_fma_f32 v38, v46, s44, -v32
	v_mfma_f32_32x32x16_bf16 v[0:15], v[108:111], v[34:37], v[0:15]
	v_exp_f32_e32 v33, v33
	v_exp_f32_e32 v39, v38
	v_fma_f32 v38, v47, s44, -v32
	v_exp_f32_e32 v45, v38
	v_add_f32_e32 v38, v33, v48
	v_mfma_f32_32x32x16_bf16 v[16:31], v[104:107], v[34:37], v[16:31]
	v_add_f32_e32 v34, v39, v38
	v_cvt_pk_bf16_f32 v36, v179, v41
	v_cvt_pk_bf16_f32 v37, v42, v43
	v_cvt_pk_bf16_f32 v38, v44, v33
	v_cvt_pk_bf16_f32 v39, v39, v45
	v_add_f32_e32 v34, v45, v34
	v_mfma_f32_32x32x16_bf16 v[0:15], v[100:103], v[36:39], v[0:15]
	s_nop 1
	v_fmac_f32_e32 v34, v175, v40
	v_mfma_f32_32x32x16_bf16 v[16:31], v[96:99], v[36:39], v[16:31]
	s_cbranch_scc1 .LBB0_337
	v_mov_b32_e32 v175, v34
	v_mov_b32_e32 v176, v32
	s_branch .LBB0_346

; DI void phase_attn_nsa(const Params& P, bf16_t* og, unsigned char* smem, int L, int G) {
;     ...
;       for (int j = jlo; j <= jhi; ++j) {
;         const int key0 = j * 64, cb = (j - jlo) & 1;
;         __syncthreads();
;         if (j < jhi) kv64_store(R, sK + (cb ^ 1) * KVB64, sVt + (cb ^ 1) * KVB64, tid);
;         if (j + 1 < jhi) kv64_fetch(R, kb, 256, vb, SEQ, key0 + 128, true, tid);
;         __builtin_amdgcn_sched_barrier(0);
;         auto mf = [&](int kk) { const int key = key0 + kk; return key <= t && key > t - 512; };
;         if (key0 + 63 > t0 || key0 <= t0 + 31 - 512) attn_step<64, true, 0>(sK + cb * KVB64, sVt + cb * KVB64, qf, o0, o1, m, l, sc, mf, lane, s, 0.f);
;         else attn_step<64, false, 0>(sK + cb * KVB64, sVt + cb * KVB64, qf, o0, o1, m, l, sc, mf, lane, s, 0.f);
;       }
.LBB0_1369:
	s_add_i32 s4, s4, 1
	s_add_i32 s0, s2, s4
	s_add_i32 s44, s44, 64
	s_add_i32 s0, s0, -1
	s_cmp_ge_u32 s0, s20
	s_cbranch_scc1 .LBB0_1273
	v_mov_b32_e32 v147, v40
	v_mov_b32_e32 v148, v0
	s_nop 1
	v_mov_b64_e32 v[122:123], v[2:3]
	v_mov_b64_e32 v[124:125], v[4:5]
	v_mov_b64_e32 v[126:127], v[6:7]
	v_mov_b64_e32 v[128:129], v[8:9]
	v_mov_b64_e32 v[130:131], v[10:11]
	v_mov_b64_e32 v[132:133], v[12:13]
	v_mov_b64_e32 v[140:141], v[14:15]
	v_mov_b64_e32 v[144:145], v[16:17]
	v_mov_b64_e32 v[108:109], v[18:19]
	v_mov_b64_e32 v[110:111], v[20:21]
	v_mov_b64_e32 v[112:113], v[22:23]
	v_mov_b64_e32 v[114:115], v[24:25]
	v_mov_b64_e32 v[116:117], v[26:27]
	v_mov_b64_e32 v[118:119], v[28:29]
	v_mov_b64_e32 v[120:121], v[30:31]
	v_mov_b64_e32 v[142:143], v[32:33]
	s_branch .LBB0_1361

; DI unsigned pack2(float a, float b) { f32x2_t v = {a, b}; bf16x2_t r = __builtin_convertvector(v, bf16x2_t); return __builtin_bit_cast(unsigned, r); }
; DI float bflo(unsigned u) { return __uint_as_float(u << 16); }
; DI float bfhi(unsigned u) { return __uint_as_float(u & 0xffff0000u); }
; DI float siluf_(float x) { return x * __builtin_amdgcn_rcpf(1.f + __expf(-x)); }
; DI void attn_write_staged(const f32x16& o0, const f32x16& o1, bf16_t* og, const bf16_t* z, size_t tok0, int head, int lane, bf16_t* wl) {
;   const int q = lane & 31, h = lane >> 5;
; #pragma unroll
;   for (int dt = 0; dt < 2; ++dt)
; #pragma unroll
;     for (int q4 = 0; q4 < 4; ++q4) {
;       const f32x16& o = dt ? o1 : o0;
;       *(uint2*)(wl + q * 72 + dt * 32 + 8 * q4 + 4 * h) = make_uint2(pack2(o[4 * q4], o[4 * q4 + 1]), pack2(o[4 * q4 + 2], o[4 * q4 + 3]));
;     }
; #pragma unroll
;   for (int k = 0; k < 4; ++k) {
;     const int ci = lane + 64 * k, row = ci >> 3, c8 = ci & 7;
;     const u32x4 ov = *(const u32x4*)(wl + row * 72 + c8 * 8);
;     const size_t off = (tok0 + row) * 1024 + head * 64 + c8 * 8;
;     const u32x4 zv = ldg16(z + off);
;     u32x4 r;
;     r.x = pack2(bflo(ov.x) * siluf_(bflo(zv.x)), bfhi(ov.x) * siluf_(bfhi(zv.x)));
;     r.y = pack2(bflo(ov.y) * siluf_(bflo(zv.y)), bfhi(ov.y) * siluf_(bfhi(zv.y)));
;     r.z = pack2(bflo(ov.z) * siluf_(bflo(zv.z)), bfhi(ov.z) * siluf_(bfhi(zv.z)));
;     r.w = pack2(bflo(ov.w) * siluf_(bflo(zv.w)), bfhi(ov.w) * siluf_(bfhi(zv.w)));
;     *(u32x4*)(og + off) = r;
;   }
; DI void phase_attn_swa(const Params& P, const float* sinks, bf16_t* og, unsigned char* smem, int L, int G) {
;     ...
;     const float il = 1.f / l;
; #pragma unroll
;     for (int q = 0; q < 16; ++q) { o0[q] *= il; o1[q] *= il; }
;     attn_write_staged(o0, o1, og, big + SW_Z, (size_t)b * SEQ + t0, head, lane, (bf16_t*)(smem + 40960) + w * (32 * 72));
.LBB0_1659:
	v_lshlrev_b32_e32 v35, 2, v169
	ds_bpermute_b32 v35, v35, v34
	s_waitcnt lgkmcnt(0)
	v_add_f32_e32 v34, v34, v35
	s_mov_b32 s11, s9
	v_lshlrev_b32_e32 v35, 6, v173
	v_lshl_add_u64 v[32:33], v[148:149], 0, s[10:11]
	v_or_b32_e32 v35, v35, v130
	v_or_b32_e32 v36, v32, v132
	v_mov_b32_e32 v37, v33
	v_lshlrev_b64 v[40:41], 11, v[36:37]
	v_lshlrev_b32_e32 v35, 1, v35
	v_or_b32_e32 v40, v40, v35
	v_lshl_add_u64 v[36:37], s[6:7], 0, v[40:41]
	v_mov_b32_e32 v254, 0x4000
	v_mov_b32_e32 v255, 0
	v_lshl_add_u64 v[248:249], v[36:37], 0, v[254:255]
	v_lshl_add_u64 v[250:251], v[248:249], 0, v[254:255]
	v_lshl_add_u64 v[252:253], v[250:251], 0, v[254:255]
	global_load_dwordx4 v[36:39], v[36:37], off
	global_load_dwordx4 v[96:99], v[248:249], off
	global_load_dwordx4 v[100:103], v[250:251], off
	global_load_dwordx4 v[104:107], v[252:253], off
	v_div_scale_f32 v42, s[0:1], v34, v34, 1.0
	v_rcp_f32_e32 v43, v42
	v_div_scale_f32 v44, vcc, 1.0, v34, 1.0
	v_add_u32_e32 v45, 0xa000, v166
	v_fma_f32 v46, -v42, v43, 1.0
	v_fmac_f32_e32 v43, v46, v43
	v_mul_f32_e32 v46, v44, v43
	v_fma_f32 v47, -v42, v46, v44
	v_fmac_f32_e32 v46, v47, v43
	v_fma_f32 v42, -v42, v46, v44
	v_div_fmas_f32 v42, v42, v43, v46
	v_div_fixup_f32 v34, v42, v34, 1.0
	v_pk_mul_f32 v[0:1], v[34:35], v[0:1] op_sel_hi:[0,1]
	v_pk_mul_f32 v[2:3], v[34:35], v[2:3] op_sel_hi:[0,1]
	v_pk_mul_f32 v[4:5], v[34:35], v[4:5] op_sel_hi:[0,1]
	v_pk_mul_f32 v[20:21], v[20:21], v[34:35] op_sel_hi:[1,0]
	v_pk_mul_f32 v[6:7], v[34:35], v[6:7] op_sel_hi:[0,1]
	v_pk_mul_f32 v[22:23], v[22:23], v[34:35] op_sel_hi:[1,0]
	v_pk_mul_f32 v[24:25], v[24:25], v[34:35] op_sel_hi:[1,0]
	v_pk_mul_f32 v[10:11], v[34:35], v[10:11] op_sel_hi:[0,1]
	v_pk_mul_f32 v[26:27], v[26:27], v[34:35] op_sel_hi:[1,0]
	v_pk_mul_f32 v[12:13], v[34:35], v[12:13] op_sel_hi:[0,1]
	v_pk_mul_f32 v[16:17], v[16:17], v[34:35] op_sel_hi:[1,0]
	v_pk_mul_f32 v[18:19], v[18:19], v[34:35] op_sel_hi:[1,0]
	v_pk_mul_f32 v[8:9], v[34:35], v[8:9] op_sel_hi:[0,1]
	v_pk_mul_f32 v[28:29], v[28:29], v[34:35] op_sel_hi:[1,0]
	v_pk_mul_f32 v[14:15], v[34:35], v[14:15] op_sel_hi:[0,1]
	v_pk_mul_f32 v[30:31], v[30:31], v[34:35] op_sel_hi:[1,0]
	v_cvt_pk_bf16_f32 v0, v0, v1
	v_cvt_pk_bf16_f32 v1, v2, v3
	v_cvt_pk_bf16_f32 v2, v4, v5
	v_cvt_pk_bf16_f32 v3, v6, v7
	v_cvt_pk_bf16_f32 v5, v10, v11
	v_cvt_pk_bf16_f32 v6, v12, v13
	v_cvt_pk_bf16_f32 v10, v20, v21
	v_cvt_pk_bf16_f32 v11, v22, v23
	v_cvt_pk_bf16_f32 v12, v24, v25
	v_cvt_pk_bf16_f32 v13, v26, v27
	v_cvt_pk_bf16_f32 v4, v8, v9
	v_cvt_pk_bf16_f32 v7, v14, v15
	v_cvt_pk_bf16_f32 v8, v16, v17
	v_cvt_pk_bf16_f32 v9, v18, v19
	v_cvt_pk_bf16_f32 v14, v28, v29
	v_cvt_pk_bf16_f32 v15, v30, v31
	ds_write2_b64 v45, v[0:1], v[2:3] offset1:2
	ds_write2_b64 v45, v[4:5], v[6:7] offset0:4 offset1:6
	ds_write2_b64 v45, v[8:9], v[10:11] offset0:8 offset1:10
	ds_write2_b64 v45, v[12:13], v[14:15] offset0:12 offset1:14
	ds_read_b128 v[0:3], v167 offset:40960
	ds_read_b128 v[4:7], v167 offset:42112
	s_add_i32 s16, s16, s74
	s_cmpk_gt_i32 s16, 0xfff
	s_waitcnt lgkmcnt(1)
	v_lshlrev_b32_e32 v8, 16, v0
	v_and_b32_e32 v9, 0xffff0000, v0
	v_lshlrev_b32_e32 v0, 16, v1
	v_and_b32_e32 v1, 0xffff0000, v1
	s_waitcnt vmcnt(3)
	v_lshlrev_b32_e32 v10, 16, v36
	v_and_b32_e32 v11, 0xffff0000, v36
	v_lshlrev_b32_e32 v12, 16, v37
	v_and_b32_e32 v13, 0xffff0000, v37
	v_mul_f32_e32 v16, 0xbfb8aa3b, v10
	v_mul_f32_e32 v17, 0xbfb8aa3b, v11
	v_mul_f32_e32 v18, 0xbfb8aa3b, v12
	v_mul_f32_e32 v19, 0xbfb8aa3b, v13
	v_exp_f32_e32 v16, v16
	v_exp_f32_e32 v17, v17
	v_exp_f32_e32 v18, v18
	v_exp_f32_e32 v19, v19
	v_lshlrev_b32_e32 v14, 16, v38
	v_and_b32_e32 v15, 0xffff0000, v38
	v_add_f32_e32 v16, 1.0, v16
	v_add_f32_e32 v17, 1.0, v17
	v_add_f32_e32 v18, 1.0, v18
	v_add_f32_e32 v19, 1.0, v19
	v_mul_f32_e32 v20, 0xbfb8aa3b, v14
	v_mul_f32_e32 v21, 0xbfb8aa3b, v15
	v_rcp_f32_e32 v16, v16
	v_rcp_f32_e32 v17, v17
	v_rcp_f32_e32 v18, v18
	v_rcp_f32_e32 v19, v19
	v_exp_f32_e32 v20, v20
	v_exp_f32_e32 v21, v21
	v_pk_mul_f32 v[10:11], v[16:17], v[10:11]
	v_pk_mul_f32 v[12:13], v[18:19], v[12:13]
	v_add_f32_e32 v20, 1.0, v20
	v_pk_mul_f32 v[8:9], v[10:11], v[8:9]
	v_pk_mul_f32 v[10:11], v[12:13], v[0:1]
	v_add_f32_e32 v1, 1.0, v21
	v_rcp_f32_e32 v20, v20
	v_rcp_f32_e32 v21, v1
	v_lshlrev_b32_e32 v12, 16, v39
	v_cvt_pk_bf16_f32 v0, v8, v9
	v_lshlrev_b32_e32 v8, 16, v2
	v_and_b32_e32 v9, 0xffff0000, v2
	v_and_b32_e32 v13, 0xffff0000, v39
	v_mul_f32_e32 v2, 0xbfb8aa3b, v12
	v_cvt_pk_bf16_f32 v1, v10, v11
	v_pk_mul_f32 v[10:11], v[20:21], v[14:15]
	v_exp_f32_e32 v2, v2
	v_mul_f32_e32 v14, 0xbfb8aa3b, v13
	v_exp_f32_e32 v14, v14
	v_pk_mul_f32 v[8:9], v[10:11], v[8:9]
	v_add_f32_e32 v2, 1.0, v2
	v_rcp_f32_e32 v10, v2
	v_add_f32_e32 v2, 1.0, v14
	v_rcp_f32_e32 v11, v2
	v_cvt_pk_bf16_f32 v2, v8, v9
	v_lshlrev_b32_e32 v8, 16, v3
	v_and_b32_e32 v9, 0xffff0000, v3
	v_pk_mul_f32 v[10:11], v[10:11], v[12:13]
	s_waitcnt lgkmcnt(0)
	v_lshlrev_b32_e32 v12, 16, v4
	v_pk_mul_f32 v[8:9], v[10:11], v[8:9]
	v_or_b32_e32 v10, v32, v136
	v_cvt_pk_bf16_f32 v3, v8, v9
	v_lshl_add_u64 v[8:9], s[94:95], 0, v[40:41]
	global_store_dwordx4 v[8:9], v[0:3], off
	v_mov_b32_e32 v11, v33
	v_and_b32_e32 v13, 0xffff0000, v4
	v_or_b32_e32 v0, v32, v134
	v_mov_b32_e32 v1, v33
	v_lshlrev_b64 v[8:9], 11, v[0:1]
	v_or_b32_e32 v8, v8, v35
	v_lshl_add_u64 v[0:1], s[6:7], 0, v[8:9]
	v_lshlrev_b32_e32 v4, 16, v5
	v_and_b32_e32 v5, 0xffff0000, v5
	v_lshlrev_b32_e32 v14, 16, v6
	v_and_b32_e32 v15, 0xffff0000, v6
	v_lshlrev_b32_e32 v6, 16, v7
	v_and_b32_e32 v7, 0xffff0000, v7
	v_lshlrev_b64 v[10:11], 11, v[10:11]
	v_lshl_add_u64 v[8:9], s[94:95], 0, v[8:9]
	v_or_b32_e32 v10, v10, v35
	v_or_b32_e32 v32, v32, v138
	s_waitcnt vmcnt(3)
; DI unsigned pack2(float a, float b) { f32x2_t v = {a, b}; bf16x2_t r = __builtin_convertvector(v, bf16x2_t); return __builtin_bit_cast(unsigned, r); }
; DI float bflo(unsigned u) { return __uint_as_float(u << 16); }
; DI float bfhi(unsigned u) { return __uint_as_float(u & 0xffff0000u); }
; DI float siluf_(float x) { return x * __builtin_amdgcn_rcpf(1.f + __expf(-x)); }
; DI void attn_write_staged(const f32x16& o0, const f32x16& o1, bf16_t* og, const bf16_t* z, size_t tok0, int head, int lane, bf16_t* wl) {
;     ...
; #pragma unroll
;   for (int k = 0; k < 4; ++k) {
;     const int ci = lane + 64 * k, row = ci >> 3, c8 = ci & 7;
;     const u32x4 ov = *(const u32x4*)(wl + row * 72 + c8 * 8);
;     const size_t off = (tok0 + row) * 1024 + head * 64 + c8 * 8;
;     const u32x4 zv = ldg16(z + off);
;     u32x4 r;
;     r.x = pack2(bflo(ov.x) * siluf_(bflo(zv.x)), bfhi(ov.x) * siluf_(bfhi(zv.x)));
;     r.y = pack2(bflo(ov.y) * siluf_(bflo(zv.y)), bfhi(ov.y) * siluf_(bfhi(zv.y)));
;     r.z = pack2(bflo(ov.z) * siluf_(bflo(zv.z)), bfhi(ov.z) * siluf_(bfhi(zv.z)));
;     r.w = pack2(bflo(ov.w) * siluf_(bflo(zv.w)), bfhi(ov.w) * siluf_(bfhi(zv.w)));
;     *(u32x4*)(og + off) = r;
;   }
	v_mov_b32_e32 v0, v96
	v_mov_b32_e32 v1, v97
	v_mov_b32_e32 v2, v98
	v_mov_b32_e32 v3, v99
	v_lshlrev_b32_e32 v16, 16, v0
	v_and_b32_e32 v17, 0xffff0000, v0
	v_lshlrev_b32_e32 v0, 16, v1
	v_and_b32_e32 v1, 0xffff0000, v1
	v_lshlrev_b32_e32 v18, 16, v2
	v_and_b32_e32 v19, 0xffff0000, v2
	v_lshlrev_b32_e32 v2, 16, v3
	v_and_b32_e32 v3, 0xffff0000, v3
	v_mul_f32_e32 v20, 0xbfb8aa3b, v16
	v_mul_f32_e32 v21, 0xbfb8aa3b, v17
	v_mul_f32_e32 v22, 0xbfb8aa3b, v0
	v_mul_f32_e32 v23, 0xbfb8aa3b, v1
	v_mul_f32_e32 v24, 0xbfb8aa3b, v18
	v_mul_f32_e32 v25, 0xbfb8aa3b, v19
	v_mul_f32_e32 v26, 0xbfb8aa3b, v2
	v_mul_f32_e32 v27, 0xbfb8aa3b, v3
	v_exp_f32_e32 v20, v20
	v_exp_f32_e32 v21, v21
	v_exp_f32_e32 v22, v22
	v_exp_f32_e32 v23, v23
	v_exp_f32_e32 v24, v24
	v_exp_f32_e32 v25, v25
	v_exp_f32_e32 v26, v26
	v_exp_f32_e32 v27, v27
	v_add_f32_e32 v20, 1.0, v20
	v_add_f32_e32 v21, 1.0, v21
	v_add_f32_e32 v22, 1.0, v22
	v_add_f32_e32 v23, 1.0, v23
	v_add_f32_e32 v24, 1.0, v24
	v_add_f32_e32 v25, 1.0, v25
	v_add_f32_e32 v26, 1.0, v26
	v_add_f32_e32 v27, 1.0, v27
	v_rcp_f32_e32 v20, v20
	v_rcp_f32_e32 v21, v21
	v_rcp_f32_e32 v22, v22
	v_rcp_f32_e32 v23, v23
	v_rcp_f32_e32 v24, v24
	v_rcp_f32_e32 v25, v25
	v_rcp_f32_e32 v26, v26
	v_rcp_f32_e32 v27, v27
	v_pk_mul_f32 v[16:17], v[20:21], v[16:17]
	v_pk_mul_f32 v[0:1], v[22:23], v[0:1]
	v_pk_mul_f32 v[18:19], v[24:25], v[18:19]
	v_pk_mul_f32 v[2:3], v[26:27], v[2:3]
	v_pk_mul_f32 v[12:13], v[16:17], v[12:13]
	v_pk_mul_f32 v[4:5], v[0:1], v[4:5]
	v_pk_mul_f32 v[14:15], v[18:19], v[14:15]
	v_pk_mul_f32 v[6:7], v[2:3], v[6:7]
	v_cvt_pk_bf16_f32 v0, v12, v13
	v_cvt_pk_bf16_f32 v1, v4, v5
	v_cvt_pk_bf16_f32 v2, v14, v15
	v_cvt_pk_bf16_f32 v3, v6, v7
	global_store_dwordx4 v[8:9], v[0:3], off
	v_lshlrev_b64 v[12:13], 11, v[32:33]
	ds_read_b128 v[4:7], v167 offset:43264
	v_lshl_add_u64 v[0:1], s[6:7], 0, v[10:11]
	v_lshl_add_u64 v[14:15], s[94:95], 0, v[10:11]
	ds_read_b128 v[8:11], v167 offset:44416
	s_waitcnt lgkmcnt(1)
	v_lshlrev_b32_e32 v18, 16, v4
	v_and_b32_e32 v19, 0xffff0000, v4
	v_lshlrev_b32_e32 v4, 16, v5
	v_and_b32_e32 v5, 0xffff0000, v5
	v_lshlrev_b32_e32 v20, 16, v6
	v_and_b32_e32 v21, 0xffff0000, v6
	v_lshlrev_b32_e32 v6, 16, v7
	v_and_b32_e32 v7, 0xffff0000, v7
	v_or_b32_e32 v12, v12, v35
	v_lshl_add_u64 v[16:17], s[6:7], 0, v[12:13]
	s_waitcnt vmcnt(3)
	v_mov_b32_e32 v0, v100
	v_mov_b32_e32 v1, v101
	v_mov_b32_e32 v2, v102
	v_mov_b32_e32 v3, v103
	v_lshlrev_b32_e32 v22, 16, v0
	v_and_b32_e32 v23, 0xffff0000, v0
	v_lshlrev_b32_e32 v0, 16, v1
	v_and_b32_e32 v1, 0xffff0000, v1
	v_lshlrev_b32_e32 v24, 16, v2
	v_and_b32_e32 v25, 0xffff0000, v2
	v_lshlrev_b32_e32 v2, 16, v3
	v_and_b32_e32 v3, 0xffff0000, v3
	v_mul_f32_e32 v26, 0xbfb8aa3b, v22
	v_mul_f32_e32 v27, 0xbfb8aa3b, v23
	v_mul_f32_e32 v28, 0xbfb8aa3b, v0
	v_mul_f32_e32 v29, 0xbfb8aa3b, v1
	v_mul_f32_e32 v30, 0xbfb8aa3b, v24
	v_mul_f32_e32 v31, 0xbfb8aa3b, v25
	v_mul_f32_e32 v32, 0xbfb8aa3b, v2
	v_mul_f32_e32 v33, 0xbfb8aa3b, v3
	v_exp_f32_e32 v26, v26
	v_exp_f32_e32 v27, v27
	v_exp_f32_e32 v28, v28
	v_exp_f32_e32 v29, v29
	v_exp_f32_e32 v30, v30
	v_exp_f32_e32 v31, v31
	v_exp_f32_e32 v32, v32
	v_exp_f32_e32 v33, v33
	v_add_f32_e32 v26, 1.0, v26
	v_add_f32_e32 v27, 1.0, v27
	v_add_f32_e32 v28, 1.0, v28
	v_add_f32_e32 v29, 1.0, v29
	v_add_f32_e32 v30, 1.0, v30
	v_add_f32_e32 v31, 1.0, v31
	v_add_f32_e32 v32, 1.0, v32
	v_add_f32_e32 v33, 1.0, v33
	v_rcp_f32_e32 v26, v26
	v_rcp_f32_e32 v27, v27
	v_rcp_f32_e32 v28, v28
	v_rcp_f32_e32 v29, v29
	v_rcp_f32_e32 v30, v30
	v_rcp_f32_e32 v31, v31
	v_rcp_f32_e32 v32, v32
	v_rcp_f32_e32 v33, v33
	v_pk_mul_f32 v[22:23], v[26:27], v[22:23]
	v_pk_mul_f32 v[0:1], v[28:29], v[0:1]
	v_pk_mul_f32 v[24:25], v[30:31], v[24:25]
	v_pk_mul_f32 v[2:3], v[32:33], v[2:3]
	v_pk_mul_f32 v[18:19], v[22:23], v[18:19]
	v_pk_mul_f32 v[4:5], v[0:1], v[4:5]
	v_pk_mul_f32 v[20:21], v[24:25], v[20:21]
	v_pk_mul_f32 v[6:7], v[2:3], v[6:7]
	v_cvt_pk_bf16_f32 v0, v18, v19
	v_cvt_pk_bf16_f32 v1, v4, v5
	v_cvt_pk_bf16_f32 v2, v20, v21
	v_cvt_pk_bf16_f32 v3, v6, v7
	global_store_dwordx4 v[14:15], v[0:3], off
	v_lshl_add_u64 v[4:5], s[94:95], 0, v[12:13]
	s_waitcnt lgkmcnt(0)
	v_lshlrev_b32_e32 v6, 16, v8
	v_and_b32_e32 v7, 0xffff0000, v8
	v_lshlrev_b32_e32 v8, 16, v9
	v_and_b32_e32 v9, 0xffff0000, v9
	v_lshlrev_b32_e32 v12, 16, v10
	v_and_b32_e32 v13, 0xffff0000, v10
	v_lshlrev_b32_e32 v10, 16, v11
	v_and_b32_e32 v11, 0xffff0000, v11
	s_waitcnt vmcnt(3)
	v_mov_b32_e32 v0, v104
	v_mov_b32_e32 v1, v105
	v_mov_b32_e32 v2, v106
	v_mov_b32_e32 v3, v107
	v_lshlrev_b32_e32 v14, 16, v0
	v_and_b32_e32 v15, 0xffff0000, v0
	v_lshlrev_b32_e32 v0, 16, v1
	v_and_b32_e32 v1, 0xffff0000, v1
	v_lshlrev_b32_e32 v16, 16, v2
	v_and_b32_e32 v17, 0xffff0000, v2
	v_lshlrev_b32_e32 v2, 16, v3
	v_and_b32_e32 v3, 0xffff0000, v3
	v_mul_f32_e32 v18, 0xbfb8aa3b, v14
	v_mul_f32_e32 v19, 0xbfb8aa3b, v15
	v_mul_f32_e32 v20, 0xbfb8aa3b, v0
	v_mul_f32_e32 v21, 0xbfb8aa3b, v1
	v_mul_f32_e32 v22, 0xbfb8aa3b, v16
	v_mul_f32_e32 v23, 0xbfb8aa3b, v17
	v_mul_f32_e32 v24, 0xbfb8aa3b, v2
	v_mul_f32_e32 v25, 0xbfb8aa3b, v3
	v_exp_f32_e32 v18, v18
	v_exp_f32_e32 v19, v19
	v_exp_f32_e32 v20, v20
	v_exp_f32_e32 v21, v21
	v_exp_f32_e32 v22, v22
	v_exp_f32_e32 v23, v23
	v_exp_f32_e32 v24, v24
	v_exp_f32_e32 v25, v25
	v_add_f32_e32 v18, 1.0, v18
	v_add_f32_e32 v19, 1.0, v19
	v_add_f32_e32 v20, 1.0, v20
	v_add_f32_e32 v21, 1.0, v21
	v_add_f32_e32 v22, 1.0, v22
	v_add_f32_e32 v23, 1.0, v23
	v_add_f32_e32 v24, 1.0, v24
	v_add_f32_e32 v25, 1.0, v25
	v_rcp_f32_e32 v18, v18
	v_rcp_f32_e32 v19, v19
	v_rcp_f32_e32 v20, v20
	v_rcp_f32_e32 v21, v21
	v_rcp_f32_e32 v22, v22
	v_rcp_f32_e32 v23, v23
	v_rcp_f32_e32 v24, v24
	v_rcp_f32_e32 v25, v25
	v_pk_mul_f32 v[14:15], v[18:19], v[14:15]
	v_pk_mul_f32 v[0:1], v[20:21], v[0:1]
	v_pk_mul_f32 v[16:17], v[22:23], v[16:17]
	v_pk_mul_f32 v[2:3], v[24:25], v[2:3]
	v_pk_mul_f32 v[6:7], v[14:15], v[6:7]
	v_pk_mul_f32 v[8:9], v[0:1], v[8:9]
	v_pk_mul_f32 v[12:13], v[16:17], v[12:13]
	v_pk_mul_f32 v[10:11], v[2:3], v[10:11]
	v_cvt_pk_bf16_f32 v0, v6, v7
	v_cvt_pk_bf16_f32 v1, v8, v9
	v_cvt_pk_bf16_f32 v2, v12, v13
	v_cvt_pk_bf16_f32 v3, v10, v11
	global_store_dwordx4 v[4:5], v[0:3], off
	s_cbranch_scc1 .LBB0_1674

; DI void phase_attn_swa(const Params& P, const float* sinks, bf16_t* og, unsigned char* smem, int L, int G) {
;     ...
;     float m = sinks[head] * LOG2E, l = 1.f;
;     const bf16_t* kb = big + SW_K + (size_t)b * SEQ * 256 + g * 64;
;     const bf16_t* vb = big + SW_VT + (size_t)((b * 4 + g) * 64) * SEQ;
;     const int jlo = (t0 - 127 > 0 ? t0 - 127 : 0) >> 6, jhi = (t0 + 31) >> 6;
;     KVR R; kv64_fetch(R, kb, 256, vb, SEQ, jlo * 64, true, tid);
;     __syncthreads();
;     kv64_store(R, sK, sVt, tid);
;     if (jlo < jhi) kv64_fetch(R, kb, 256, vb, SEQ, jlo * 64 + 64, true, tid);
.LBB0_1666:
	s_cmp_gt_u32 s17, s11
	s_cbranch_scc1 .LBB0_1658
	v_cmp_lt_i32_e32 vcc, v169, v170
	v_lshl_add_u64 v[152:153], v[0:1], 0, v[142:143]
	v_lshl_add_u64 v[154:155], v[2:3], 0, v[142:143]
	v_cndmask_b32_e32 v0, v168, v169, vcc
	v_lshlrev_b32_e32 v174, 2, v0
	v_mov_b32_e32 v0, 0
	v_lshl_add_u64 v[156:157], v[4:5], 0, v[142:143]
	v_mul_f32_e32 v176, 0x3fb8aa3b, v10
	v_add_u32_e32 v151, 0xffffff80, v150
	s_mov_b32 s18, 0
	s_lshl_b32 s8, s17, 6
	v_mov_b32_e32 v175, 0.5
	v_mov_b32_e32 v1, v0
	v_mov_b32_e32 v2, v0
	v_mov_b32_e32 v3, v0
	v_mov_b32_e32 v4, v0
	v_mov_b32_e32 v5, v0
	v_mov_b32_e32 v6, v0
	v_mov_b32_e32 v7, v0
	v_mov_b32_e32 v8, v0
	v_mov_b32_e32 v9, v0
	v_mov_b32_e32 v10, v0
	v_mov_b32_e32 v11, v0
	v_mov_b32_e32 v12, v0
	v_mov_b32_e32 v13, v0
	v_mov_b32_e32 v14, v0
	v_mov_b32_e32 v15, v0
	v_mov_b32_e32 v16, v0
	v_mov_b32_e32 v17, v0
	v_mov_b32_e32 v18, v0
	v_mov_b32_e32 v19, v0
	v_mov_b32_e32 v20, v0
	v_mov_b32_e32 v21, v0
	v_mov_b32_e32 v22, v0
	v_mov_b32_e32 v23, v0
	v_mov_b32_e32 v24, v0
	v_mov_b32_e32 v25, v0
	v_mov_b32_e32 v26, v0
	v_mov_b32_e32 v27, v0
	v_mov_b32_e32 v28, v0
	v_mov_b32_e32 v29, v0
	v_mov_b32_e32 v30, v0
	v_mov_b32_e32 v31, v0

; #define MFMA(a, b, c) __builtin_amdgcn_mfma_f32_32x32x16_bf16((a), (b), (c), 0, 0, 0)
; template <int DQK, bool MASKED, int MODE, class MF>
; DI void attn_step(const bf16_t* sK, const bf16_t* sVt, const bf16x8 (&qf)[DQK / 16], f32x16& o0, f32x16& o1, float& m, float& l,
;                   float sc, const MF& mf, int lane, f32x16 (&s)[2], float invl, bool lanevalid = true) {
;     ...
;   bf16x8 kf[2][DQK / 16];
; #pragma unroll
;   for (int sub = 0; sub < 2; ++sub)
; #pragma unroll
;     for (int ks = 0; ks < DQK / 16; ++ks) kf[sub][ks] = *(const bf16x8*)(sK + (sub * 32 + pr) * KST + ks * 16 + 8 * h);
;   __builtin_amdgcn_sched_barrier(0);
; #pragma unroll
;   for (int q = 0; q < 16; ++q) { s[0][q] = 0.f; s[1][q] = 0.f; }
; #pragma unroll
;   for (int ks = 0; ks < DQK / 16; ++ks) {
;     s[0] = MFMA(kf[0][ks], qf[ks], s[0]);
;     s[1] = MFMA(kf[1][ks], qf[ks], s[1]);
;   }
;   bf16x8 vf[2][2][2];
;   if (MODE != 1) {
; #pragma unroll
;     for (int sub = 0; sub < 2; ++sub)
; #pragma unroll
;       for (int s2 = 0; s2 < 2; ++s2) {
;         vf[sub][s2][0] = *(const bf16x8*)(sVt + r * 72 + sub * 32 + s2 * 16 + 8 * h);
;         vf[sub][s2][1] = *(const bf16x8*)(sVt + (32 + r) * 72 + sub * 32 + s2 * 16 + 8 * h);
;       }
;     __builtin_amdgcn_sched_barrier(0);
;   }
;   float mxr = -3.0e38f;
; #pragma unroll
;   for (int sub = 0; sub < 2; ++sub)
; #pragma unroll
;     for (int q = 0; q < 16; ++q) {
;       if (MASKED) { const int kk = sub * 32 + 16 * (q >> 3) + 8 * h + (q & 7); s[sub][q] = mf(kk) ? s[sub][q] : -3.0e38f; }
;       if (MODE != 2) mxr = fmaxf(mxr, s[sub][q]);
;     }
.LBB0_1672:
	s_mulk_i32 s0, 0x4800
	v_add_u32_e32 v40, s0, v163
	ds_read_b128 v[32:35], v40
	ds_read_b128 v[96:99], v40 offset:32
	ds_read_b128 v[100:103], v40 offset:64
	ds_read_b128 v[104:107], v40 offset:96
	ds_read_b128 v[36:39], v40 offset:4608
	ds_read_b128 v[108:111], v40 offset:4640
	ds_read_b128 v[112:115], v40 offset:4672
	ds_read_b128 v[178:181], v40 offset:4704
	v_add_u32_e32 v116, s0, v137
	s_waitcnt lgkmcnt(7)
	v_mfma_f32_32x32x16_bf16 v[48:63], v[32:35], v[64:67], 0
	s_waitcnt lgkmcnt(3)
	v_mfma_f32_32x32x16_bf16 v[32:47], v[36:39], v[64:67], 0
	v_mfma_f32_32x32x16_bf16 v[48:63], v[96:99], v[68:71], v[48:63]
	v_add3_u32 v96, v116, v164, v171
	v_add3_u32 v97, v116, v165, v171
	s_waitcnt lgkmcnt(2)
	v_mfma_f32_32x32x16_bf16 v[32:47], v[108:111], v[68:71], v[32:47]
	v_mfma_f32_32x32x16_bf16 v[48:63], v[100:103], v[72:75], v[48:63]
	s_waitcnt lgkmcnt(1)
	v_mfma_f32_32x32x16_bf16 v[32:47], v[112:115], v[72:75], v[32:47]
	v_mfma_f32_32x32x16_bf16 v[48:63], v[104:107], v[76:79], v[48:63]
	ds_read_b128 v[124:127], v96 offset:9216
	ds_read_b128 v[116:119], v96 offset:9248
	ds_read_b128 v[120:123], v97 offset:9216
	ds_read_b128 v[112:115], v97 offset:9248
	ds_read_b128 v[108:111], v96 offset:9280
	ds_read_b128 v[100:103], v96 offset:9312
	ds_read_b128 v[104:107], v97 offset:9280
	ds_read_b128 v[96:99], v97 offset:9312
	s_waitcnt lgkmcnt(8)
	v_mfma_f32_32x32x16_bf16 v[32:47], v[178:181], v[76:79], v[32:47]
	v_add_u32_e32 v128, s8, v162
	v_cmp_le_u32_e32 vcc, v128, v150
	v_cmp_gt_i32_e64 s[0:1], v128, v151
	s_and_b64 vcc, vcc, s[0:1]
	v_cndmask_b32_e32 v48, v172, v48, vcc
	v_cmp_lt_u32_e32 vcc, v128, v150
	v_cmp_ge_i32_e64 s[0:1], v128, v151
	s_and_b64 vcc, vcc, s[0:1]
	v_add_u32_e32 v177, 2, v128
	v_cndmask_b32_e32 v49, v172, v49, vcc
	v_cmp_le_u32_e32 vcc, v177, v150
	v_cmp_gt_i32_e64 s[0:1], v177, v151
	s_and_b64 vcc, vcc, s[0:1]
	v_add_u32_e32 v177, 3, v128
	v_cndmask_b32_e32 v50, v172, v50, vcc
	v_cmp_le_u32_e32 vcc, v177, v150
	v_cmp_gt_i32_e64 s[0:1], v177, v151
	s_and_b64 vcc, vcc, s[0:1]
	v_add_u32_e32 v177, 4, v128
	v_cndmask_b32_e32 v51, v172, v51, vcc
	v_cmp_le_u32_e32 vcc, v177, v150
	v_cmp_gt_i32_e64 s[0:1], v177, v151
	s_and_b64 vcc, vcc, s[0:1]
	v_add_u32_e32 v177, 5, v128
	v_cndmask_b32_e32 v52, v172, v52, vcc
	v_cmp_le_u32_e32 vcc, v177, v150
	v_cmp_gt_i32_e64 s[0:1], v177, v151
	s_and_b64 vcc, vcc, s[0:1]
	v_add_u32_e32 v177, 6, v128
	v_cndmask_b32_e32 v53, v172, v53, vcc
	v_cmp_le_u32_e32 vcc, v177, v150
	v_cmp_gt_i32_e64 s[0:1], v177, v151
	v_add_u32_e32 v177, s8, v161
	s_and_b64 vcc, vcc, s[0:1]
	v_or_b32_e32 v178, 7, v177
	v_cndmask_b32_e32 v54, v172, v54, vcc
	v_cmp_le_u32_e32 vcc, v178, v150
	v_cmp_gt_i32_e64 s[0:1], v178, v151
	s_and_b64 vcc, vcc, s[0:1]
	v_add_u32_e32 v178, 16, v128
	v_cndmask_b32_e32 v55, v172, v55, vcc
	v_cmp_le_u32_e32 vcc, v178, v150
	v_cmp_gt_i32_e64 s[0:1], v178, v151
	s_and_b64 vcc, vcc, s[0:1]
	v_add_u32_e32 v178, 17, v128
	v_cndmask_b32_e32 v56, v172, v56, vcc
	v_cmp_le_u32_e32 vcc, v178, v150
	v_cmp_gt_i32_e64 s[0:1], v178, v151
	s_and_b64 vcc, vcc, s[0:1]
	v_add_u32_e32 v178, 18, v128
	v_cndmask_b32_e32 v57, v172, v57, vcc
	v_cmp_le_u32_e32 vcc, v178, v150
	v_cmp_gt_i32_e64 s[0:1], v178, v151
	s_and_b64 vcc, vcc, s[0:1]
	v_add_u32_e32 v178, 19, v128
	v_cndmask_b32_e32 v58, v172, v58, vcc
	v_cmp_le_u32_e32 vcc, v178, v150
	v_cmp_gt_i32_e64 s[0:1], v178, v151
	s_and_b64 vcc, vcc, s[0:1]
	v_add_u32_e32 v178, 20, v128
	v_cndmask_b32_e32 v59, v172, v59, vcc
	v_cmp_le_u32_e32 vcc, v178, v150
	v_cmp_gt_i32_e64 s[0:1], v178, v151
	s_and_b64 vcc, vcc, s[0:1]
	v_add_u32_e32 v178, 21, v128
	v_cndmask_b32_e32 v60, v172, v60, vcc
	v_cmp_le_u32_e32 vcc, v178, v150
	v_cmp_gt_i32_e64 s[0:1], v178, v151
	s_and_b64 vcc, vcc, s[0:1]
	v_add_u32_e32 v178, 22, v128
	v_cndmask_b32_e32 v61, v172, v61, vcc
	v_cmp_le_u32_e32 vcc, v178, v150
	v_cmp_gt_i32_e64 s[0:1], v178, v151
	s_and_b64 vcc, vcc, s[0:1]
	v_or_b32_e32 v178, 23, v177
	v_cndmask_b32_e32 v62, v172, v62, vcc
	v_cmp_le_u32_e32 vcc, v178, v150
	v_cmp_gt_i32_e64 s[0:1], v178, v151
	s_and_b64 vcc, vcc, s[0:1]
	v_add_u32_e32 v178, 32, v128
	v_cndmask_b32_e32 v63, v172, v63, vcc
	v_cmp_le_u32_e32 vcc, v178, v150
	v_cmp_gt_i32_e64 s[0:1], v178, v151
	s_and_b64 vcc, vcc, s[0:1]
	v_cndmask_b32_e32 v178, v172, v32, vcc
	v_add_u32_e32 v32, 33, v128
	v_cmp_le_u32_e32 vcc, v32, v150
	v_cmp_gt_i32_e64 s[0:1], v32, v151
	s_and_b64 vcc, vcc, s[0:1]
	v_add_u32_e32 v32, 34, v128
	v_cndmask_b32_e32 v33, v172, v33, vcc
	v_cmp_le_u32_e32 vcc, v32, v150
	v_cmp_gt_i32_e64 s[0:1], v32, v151
	s_and_b64 vcc, vcc, s[0:1]
	v_add_u32_e32 v32, 35, v128
	v_cndmask_b32_e32 v34, v172, v34, vcc
	v_cmp_le_u32_e32 vcc, v32, v150
	v_cmp_gt_i32_e64 s[0:1], v32, v151
	s_and_b64 vcc, vcc, s[0:1]
	v_add_u32_e32 v32, 36, v128
	v_cndmask_b32_e32 v35, v172, v35, vcc
	v_cmp_le_u32_e32 vcc, v32, v150
	v_cmp_gt_i32_e64 s[0:1], v32, v151
	s_and_b64 vcc, vcc, s[0:1]
	v_add_u32_e32 v32, 37, v128
	v_cndmask_b32_e32 v36, v172, v36, vcc
	v_cmp_le_u32_e32 vcc, v32, v150
	v_cmp_gt_i32_e64 s[0:1], v32, v151
	s_and_b64 vcc, vcc, s[0:1]
	v_add_u32_e32 v32, 38, v128
	v_cndmask_b32_e32 v37, v172, v37, vcc
	v_cmp_le_u32_e32 vcc, v32, v150
	v_cmp_gt_i32_e64 s[0:1], v32, v151
	s_and_b64 vcc, vcc, s[0:1]
	v_or_b32_e32 v32, 39, v177
	v_cndmask_b32_e32 v38, v172, v38, vcc
	v_cmp_le_u32_e32 vcc, v32, v150
	v_cmp_gt_i32_e64 s[0:1], v32, v151
	s_and_b64 vcc, vcc, s[0:1]
	v_add_u32_e32 v32, 48, v128
	v_cndmask_b32_e32 v39, v172, v39, vcc
	v_cmp_le_u32_e32 vcc, v32, v150
	v_cmp_gt_i32_e64 s[0:1], v32, v151
	s_and_b64 vcc, vcc, s[0:1]
	v_add_u32_e32 v32, 49, v128
	v_cndmask_b32_e32 v179, v172, v40, vcc
; #define MFMA(a, b, c) __builtin_amdgcn_mfma_f32_32x32x16_bf16((a), (b), (c), 0, 0, 0)
; DI unsigned pack2(float a, float b) { f32x2_t v = {a, b}; bf16x2_t r = __builtin_convertvector(v, bf16x2_t); return __builtin_bit_cast(unsigned, r); }
; DI float fexp2(float x) { return __builtin_amdgcn_exp2f(x); }
; DI float shx(float v, int m) { return __shfl_xor(v, m, 64); }
; template <int DQK, bool MASKED, int MODE, class MF>
; DI void attn_step(const bf16_t* sK, const bf16_t* sVt, const bf16x8 (&qf)[DQK / 16], f32x16& o0, f32x16& o1, float& m, float& l,
;                   float sc, const MF& mf, int lane, f32x16 (&s)[2], float invl, bool lanevalid = true) {
;     ...
;   float mxr = -3.0e38f;
; #pragma unroll
;   for (int sub = 0; sub < 2; ++sub)
; #pragma unroll
;     for (int q = 0; q < 16; ++q) {
;       if (MASKED) { const int kk = sub * 32 + 16 * (q >> 3) + 8 * h + (q & 7); s[sub][q] = mf(kk) ? s[sub][q] : -3.0e38f; }
;       if (MODE != 2) mxr = fmaxf(mxr, s[sub][q]);
;     }
;   float alpha = 1.f;
;   if (MODE != 2) {
;     float mx = fmaxf(m, mxr * sc);
;     mx = fmaxf(mx, shx(mx, 32));
;     if (!MASKED) mx = lanevalid ? mx : m;
;     alpha = fexp2(m - mx);
;     m = mx;
;   }
;   const float moff = (!MASKED && !lanevalid) ? 1.0e30f : m;
;   float ps = 0.f;
; #pragma unroll
;   for (int sub = 0; sub < 2; ++sub)
; #pragma unroll
;     for (int q = 0; q < 16; ++q) {
;       float pv = fexp2(__builtin_fmaf(s[sub][q], sc, -moff));
;       if (MASKED && MODE != 0) pv = (s[sub][q] > -1.0e38f) ? pv : 0.f;
;       if (MODE == 2) pv *= invl;
;       s[sub][q] = pv;
;       ps += pv;
;     }
;   if (MODE != 2) {
;     ps += shx(ps, 32);
;     l = l * alpha + ps;
;   }
;   if (MODE == 1) return;
;   if (MODE == 0) {
; #pragma unroll
;     for (int q = 0; q < 16; ++q) { o0[q] *= alpha; o1[q] *= alpha; }
;   }
; #pragma unroll
;   for (int sub = 0; sub < 2; ++sub)
; #pragma unroll
;     for (int s2 = 0; s2 < 2; ++s2) {
;       union { bf16x8 v; unsigned u[4]; } pb;
; #pragma unroll
;       for (int e = 0; e < 4; ++e) pb.u[e] = pack2(s[sub][8 * s2 + 2 * e], s[sub][8 * s2 + 2 * e + 1]);
;       o0 = MFMA(vf[sub][s2][0], pb.v, o0);
;       o1 = MFMA(vf[sub][s2][1], pb.v, o1);
;     }
	v_cmp_le_u32_e32 vcc, v32, v150
	v_cmp_gt_i32_e64 s[0:1], v32, v151
	s_and_b64 vcc, vcc, s[0:1]
	v_add_u32_e32 v32, 50, v128
	v_cndmask_b32_e32 v41, v172, v41, vcc
	v_cmp_le_u32_e32 vcc, v32, v150
	v_cmp_gt_i32_e64 s[0:1], v32, v151
	s_and_b64 vcc, vcc, s[0:1]
	v_add_u32_e32 v32, 51, v128
	v_cndmask_b32_e32 v42, v172, v42, vcc
	v_cmp_le_u32_e32 vcc, v32, v150
	v_cmp_gt_i32_e64 s[0:1], v32, v151
	s_and_b64 vcc, vcc, s[0:1]
	v_add_u32_e32 v32, 52, v128
	v_cndmask_b32_e32 v43, v172, v43, vcc
	v_cmp_le_u32_e32 vcc, v32, v150
	v_cmp_gt_i32_e64 s[0:1], v32, v151
	s_and_b64 vcc, vcc, s[0:1]
	v_add_u32_e32 v32, 53, v128
	v_cndmask_b32_e32 v44, v172, v44, vcc
	v_cmp_le_u32_e32 vcc, v32, v150
	v_cmp_gt_i32_e64 s[0:1], v32, v151
	s_and_b64 vcc, vcc, s[0:1]
	v_add_u32_e32 v32, 54, v128
	v_cndmask_b32_e32 v45, v172, v45, vcc
	v_cmp_le_u32_e32 vcc, v32, v150
	v_cmp_gt_i32_e64 s[0:1], v32, v151
	s_and_b64 vcc, vcc, s[0:1]
	v_or_b32_e32 v32, 55, v177
	v_cndmask_b32_e32 v46, v172, v46, vcc
	v_cmp_le_u32_e32 vcc, v32, v150
	v_cmp_gt_i32_e64 s[0:1], v32, v151
	v_max3_f32 v32, v48, s14, v49
	v_max3_f32 v32, v32, v50, v51
	v_max3_f32 v32, v32, v52, v53
	v_max3_f32 v32, v32, v54, v55
	v_max3_f32 v32, v32, v56, v57
	v_max3_f32 v32, v32, v58, v59
	v_max3_f32 v32, v32, v60, v61
	v_max3_f32 v32, v32, v62, v63
	v_max3_f32 v32, v32, v178, v33
	v_max3_f32 v32, v32, v34, v35
	v_max3_f32 v32, v32, v36, v37
	v_max3_f32 v32, v32, v38, v39
	v_max3_f32 v32, v32, v179, v41
	s_and_b64 vcc, vcc, s[0:1]
	v_max3_f32 v32, v32, v42, v43
	v_cndmask_b32_e32 v47, v172, v47, vcc
	v_max3_f32 v32, v32, v44, v45
	v_max3_f32 v32, v32, v46, v47
	v_mul_f32_e32 v32, 0x3e38aa3b, v32
	v_max_f32_e32 v40, v176, v176
	v_max_f32_e32 v32, v40, v32
	ds_bpermute_b32 v40, v174, v32
	s_add_i32 s18, s18, 1
	s_add_i32 s0, s17, s18
	s_add_i32 s8, s8, 64
	s_add_i32 s0, s0, -1
	s_waitcnt lgkmcnt(0)
	v_max_f32_e32 v40, v40, v40
	v_max_f32_e32 v32, v32, v40
	v_fma_f32 v40, v48, s15, -v32
	v_exp_f32_e32 v48, v40
	v_fma_f32 v49, v49, s15, -v32
	v_exp_f32_e32 v49, v49
	v_fma_f32 v50, v50, s15, -v32
	v_exp_f32_e32 v50, v50
	v_fma_f32 v51, v51, s15, -v32
	v_exp_f32_e32 v51, v51
	v_fma_f32 v52, v52, s15, -v32
	v_add_f32_e32 v128, 0, v48
	v_exp_f32_e32 v52, v52
	v_fma_f32 v53, v53, s15, -v32
	v_add_f32_e32 v128, v49, v128
	v_exp_f32_e32 v53, v53
	v_fma_f32 v54, v54, s15, -v32
	v_add_f32_e32 v128, v50, v128
	v_exp_f32_e32 v54, v54
	v_fma_f32 v55, v55, s15, -v32
	v_add_f32_e32 v128, v51, v128
	v_exp_f32_e32 v55, v55
	v_fma_f32 v56, v56, s15, -v32
	v_add_f32_e32 v128, v52, v128
	v_exp_f32_e32 v56, v56
	v_fma_f32 v57, v57, s15, -v32
	v_add_f32_e32 v128, v53, v128
	v_exp_f32_e32 v57, v57
	v_fma_f32 v58, v58, s15, -v32
	v_add_f32_e32 v128, v54, v128
	v_exp_f32_e32 v58, v58
	v_fma_f32 v59, v59, s15, -v32
	v_add_f32_e32 v128, v55, v128
	v_exp_f32_e32 v59, v59
	v_fma_f32 v60, v60, s15, -v32
	v_add_f32_e32 v128, v56, v128
	v_exp_f32_e32 v60, v60
	v_fma_f32 v61, v61, s15, -v32
	v_add_f32_e32 v128, v57, v128
	v_exp_f32_e32 v61, v61
	v_fma_f32 v62, v62, s15, -v32
	v_add_f32_e32 v128, v58, v128
	v_exp_f32_e32 v62, v62
	v_fma_f32 v63, v63, s15, -v32
	v_sub_f32_e32 v40, v176, v32
	v_add_f32_e32 v128, v59, v128
	v_exp_f32_e32 v63, v63
	v_fma_f32 v176, v178, s15, -v32
	v_add_f32_e32 v128, v60, v128
	v_exp_f32_e32 v176, v176
	v_fma_f32 v33, v33, s15, -v32
	v_add_f32_e32 v128, v61, v128
	v_exp_f32_e32 v33, v33
	v_fma_f32 v34, v34, s15, -v32
	v_add_f32_e32 v128, v62, v128
	v_exp_f32_e32 v177, v34
	v_fma_f32 v34, v35, s15, -v32
	v_add_f32_e32 v128, v63, v128
	v_exp_f32_e32 v178, v34
	v_fma_f32 v34, v36, s15, -v32
	v_add_f32_e32 v128, v176, v128
	v_exp_f32_e32 v180, v34
	v_fma_f32 v35, v37, s15, -v32
	v_add_f32_e32 v34, v33, v128
	v_exp_f32_e32 v128, v35
	v_fma_f32 v35, v38, s15, -v32
	v_add_f32_e32 v34, v177, v34
	v_exp_f32_e32 v38, v35
	v_fma_f32 v35, v39, s15, -v32
	v_add_f32_e32 v34, v178, v34
	v_exp_f32_e32 v39, v35
	v_add_f32_e32 v34, v180, v34
	v_exp_f32_e32 v40, v40
	v_add_f32_e32 v34, v128, v34
	v_add_f32_e32 v34, v38, v34
	v_add_f32_e32 v181, v39, v34
	v_fma_f32 v34, v179, s15, -v32
	v_exp_f32_e32 v179, v34
	v_pk_mul_f32 v[14:15], v[14:15], v[40:41] op_sel_hi:[1,0]
	v_pk_mul_f32 v[12:13], v[12:13], v[40:41] op_sel_hi:[1,0]
	v_pk_mul_f32 v[10:11], v[10:11], v[40:41] op_sel_hi:[1,0]
	v_pk_mul_f32 v[8:9], v[8:9], v[40:41] op_sel_hi:[1,0]
	v_pk_mul_f32 v[6:7], v[6:7], v[40:41] op_sel_hi:[1,0]
	v_pk_mul_f32 v[4:5], v[4:5], v[40:41] op_sel_hi:[1,0]
	v_pk_mul_f32 v[2:3], v[2:3], v[40:41] op_sel_hi:[1,0]
	v_pk_mul_f32 v[0:1], v[0:1], v[40:41] op_sel_hi:[1,0]
	v_pk_mul_f32 v[30:31], v[30:31], v[40:41] op_sel_hi:[1,0]
	v_cvt_pk_bf16_f32 v34, v48, v49
	v_cvt_pk_bf16_f32 v35, v50, v51
	v_cvt_pk_bf16_f32 v36, v52, v53
	v_cvt_pk_bf16_f32 v37, v54, v55
	v_pk_mul_f32 v[28:29], v[28:29], v[40:41] op_sel_hi:[1,0]
	v_pk_mul_f32 v[26:27], v[26:27], v[40:41] op_sel_hi:[1,0]
	v_pk_mul_f32 v[24:25], v[24:25], v[40:41] op_sel_hi:[1,0]
	v_pk_mul_f32 v[22:23], v[22:23], v[40:41] op_sel_hi:[1,0]
	v_pk_mul_f32 v[20:21], v[20:21], v[40:41] op_sel_hi:[1,0]
	v_pk_mul_f32 v[18:19], v[18:19], v[40:41] op_sel_hi:[1,0]
	v_pk_mul_f32 v[16:17], v[16:17], v[40:41] op_sel_hi:[1,0]
	v_mfma_f32_32x32x16_bf16 v[0:15], v[124:127], v[34:37], v[0:15]
	v_fma_f32 v42, v42, s15, -v32
	v_exp_f32_e32 v42, v42
	v_fma_f32 v43, v43, s15, -v32
	v_exp_f32_e32 v43, v43
	v_fma_f32 v44, v44, s15, -v32
	v_add_f32_e32 v48, v179, v181
	v_exp_f32_e32 v44, v44
	v_mfma_f32_32x32x16_bf16 v[16:31], v[120:123], v[34:37], v[16:31]
	v_fma_f32 v34, v41, s15, -v32
	v_exp_f32_e32 v41, v34
	v_cvt_pk_bf16_f32 v34, v56, v57
	v_cvt_pk_bf16_f32 v35, v58, v59
	v_cvt_pk_bf16_f32 v36, v60, v61
	v_cvt_pk_bf16_f32 v37, v62, v63
	v_add_f32_e32 v48, v41, v48
	s_cmp_ge_u32 s0, s11
	v_mfma_f32_32x32x16_bf16 v[0:15], v[116:119], v[34:37], v[0:15]
	v_mfma_f32_32x32x16_bf16 v[16:31], v[112:115], v[34:37], v[16:31]
	v_add_f32_e32 v34, v42, v48
	v_add_f32_e32 v34, v43, v34
	v_add_f32_e32 v48, v44, v34
	v_cvt_pk_bf16_f32 v34, v176, v33
	v_cvt_pk_bf16_f32 v35, v177, v178
	v_cvt_pk_bf16_f32 v36, v180, v128
	v_cvt_pk_bf16_f32 v37, v38, v39
	v_fma_f32 v33, v45, s15, -v32
	v_fma_f32 v38, v46, s15, -v32
	v_mfma_f32_32x32x16_bf16 v[0:15], v[108:111], v[34:37], v[0:15]
	v_exp_f32_e32 v33, v33
	v_exp_f32_e32 v39, v38
	v_fma_f32 v38, v47, s15, -v32
	v_exp_f32_e32 v45, v38
	v_add_f32_e32 v38, v33, v48
	v_mfma_f32_32x32x16_bf16 v[16:31], v[104:107], v[34:37], v[16:31]
	v_add_f32_e32 v34, v39, v38
	v_cvt_pk_bf16_f32 v36, v179, v41
	v_cvt_pk_bf16_f32 v37, v42, v43
	v_cvt_pk_bf16_f32 v38, v44, v33
	v_cvt_pk_bf16_f32 v39, v39, v45
	v_add_f32_e32 v34, v45, v34
	v_mfma_f32_32x32x16_bf16 v[0:15], v[100:103], v[36:39], v[0:15]
	s_nop 1
	v_fmac_f32_e32 v34, v175, v40
	v_mfma_f32_32x32x16_bf16 v[16:31], v[96:99], v[36:39], v[16:31]
	s_cbranch_scc1 .LBB0_1659
	v_mov_b32_e32 v175, v34
	v_mov_b32_e32 v176, v32
	s_branch .LBB0_1668
